# v31 + gate epilogue: the 32 final-step ds_bpermute broadcasts feeding the aggregate stores replaced by plain moves (only the source lane stores)
# baseline (speedup 1.0000x reference)
.LBB0_435:
	s_waitcnt vmcnt(0) lgkmcnt(0)
	v_pk_fma_f32 v[150:151], v[150:151], s[36:37], v[94:95] op_sel_hi:[1,0,1] neg_lo:[1,0,0] neg_hi:[1,0,0]
	v_pk_fma_f32 v[148:149], v[148:149], s[36:37], v[92:93] op_sel_hi:[1,0,1] neg_lo:[1,0,0] neg_hi:[1,0,0]
	v_exp_f32_e32 v150, v150
	v_exp_f32_e32 v151, v151
	v_exp_f32_e32 v148, v148
	v_exp_f32_e32 v149, v149
	v_pk_fma_f32 v[146:147], v[146:147], s[36:37], v[86:87] op_sel_hi:[1,0,1] neg_lo:[1,0,0] neg_hi:[1,0,0]
	v_pk_add_f32 v[150:151], v[150:151], 1.0 op_sel_hi:[1,0]
	v_exp_f32_e32 v146, v146
	v_exp_f32_e32 v147, v147
	v_rcp_f32_e32 v150, v150
	v_rcp_f32_e32 v151, v151
	v_pk_add_f32 v[148:149], v[148:149], 1.0 op_sel_hi:[1,0]
	v_pk_add_f32 v[146:147], v[146:147], 1.0 op_sel_hi:[1,0]
	v_rcp_f32_e32 v148, v148
	v_rcp_f32_e32 v149, v149
	v_rcp_f32_e32 v202, v146
	v_rcp_f32_e32 v203, v147
	v_pk_mul_f32 v[146:147], v[90:91], v[150:151]
	v_pk_fma_f32 v[144:145], v[144:145], s[36:37], v[84:85] op_sel_hi:[1,0,1] neg_lo:[1,0,0] neg_hi:[1,0,0]
	v_pk_fma_f32 v[140:141], v[140:141], s[36:37], v[92:93] op_sel_hi:[1,0,1] neg_lo:[1,0,0] neg_hi:[1,0,0]
	v_exp_f32_e32 v146, v146
	v_exp_f32_e32 v147, v147
	v_exp_f32_e32 v204, v144
	v_exp_f32_e32 v205, v145
	v_pk_mul_f32 v[144:145], v[88:89], v[148:149]
	v_exp_f32_e32 v140, v140
	v_exp_f32_e32 v141, v141
	v_exp_f32_e32 v144, v144
	v_exp_f32_e32 v145, v145
	v_pk_fma_f32 v[150:151], v[146:147], v[146:147], 1.0 op_sel_hi:[1,1,0] neg_lo:[1,0,0] neg_hi:[1,0,0]
	v_pk_add_f32 v[148:149], v[204:205], 1.0 op_sel_hi:[1,0]
	v_pk_add_f32 v[140:141], v[140:141], 1.0 op_sel_hi:[1,0]
	v_sqrt_f32_e32 v150, v150
	v_sqrt_f32_e32 v151, v151
	v_rcp_f32_e32 v204, v148
	v_rcp_f32_e32 v205, v149
	v_pk_fma_f32 v[148:149], v[144:145], v[144:145], 1.0 op_sel_hi:[1,1,0] neg_lo:[1,0,0] neg_hi:[1,0,0]
	v_rcp_f32_e32 v140, v140
	v_rcp_f32_e32 v141, v141
	v_lshl_add_u32 v200, v217, 4, v215
	v_sqrt_f32_e32 v206, v148
	v_sqrt_f32_e32 v207, v149
	v_pk_fma_f32 v[142:143], v[142:143], s[36:37], v[94:95] op_sel_hi:[1,0,1] neg_lo:[1,0,0] neg_hi:[1,0,0]
	v_and_b32_e32 v223, 48, v200
	v_lshlrev_b32_e32 v200, 16, v188
	v_and_b32_e32 v201, 0xffff0000, v188
	v_lshlrev_b32_e32 v188, 16, v189
	v_and_b32_e32 v189, 0xffff0000, v189
	v_exp_f32_e32 v142, v142
	v_exp_f32_e32 v143, v143
	v_pk_mul_f32 v[148:149], v[202:203], v[188:189]
	v_pk_fma_f32 v[138:139], v[138:139], s[36:37], v[86:87] op_sel_hi:[1,0,1] neg_lo:[1,0,0] neg_hi:[1,0,0]
	v_pk_fma_f32 v[136:137], v[136:137], s[36:37], v[84:85] op_sel_hi:[1,0,1] neg_lo:[1,0,0] neg_hi:[1,0,0]
	v_pk_fma_f32 v[134:135], v[134:135], s[36:37], v[94:95] op_sel_hi:[1,0,1] neg_lo:[1,0,0] neg_hi:[1,0,0]
	v_pk_mul_f32 v[148:149], v[148:149], v[150:151]
	v_pk_mul_f32 v[150:151], v[204:205], v[200:201]
	v_exp_f32_e32 v138, v138
	v_exp_f32_e32 v139, v139
	v_exp_f32_e32 v136, v136
	v_exp_f32_e32 v137, v137
	v_pk_mul_f32 v[140:141], v[88:89], v[140:141]
	v_exp_f32_e32 v134, v134
	v_exp_f32_e32 v135, v135
	v_pk_mul_f32 v[150:151], v[150:151], v[206:207]
	v_exp_f32_e32 v206, v140
	v_exp_f32_e32 v207, v141
	v_pk_add_f32 v[142:143], v[142:143], 1.0 op_sel_hi:[1,0]
	v_pk_fma_f32 v[132:133], v[132:133], s[36:37], v[92:93] op_sel_hi:[1,0,1] neg_lo:[1,0,0] neg_hi:[1,0,0]
	v_rcp_f32_e32 v142, v142
	v_rcp_f32_e32 v143, v143
	v_exp_f32_e32 v132, v132
	v_exp_f32_e32 v133, v133
	v_pk_add_f32 v[138:139], v[138:139], 1.0 op_sel_hi:[1,0]
	v_pk_add_f32 v[136:137], v[136:137], 1.0 op_sel_hi:[1,0]
	v_pk_add_f32 v[134:135], v[134:135], 1.0 op_sel_hi:[1,0]
	v_pk_fma_f32 v[124:125], v[124:125], s[36:37], v[92:93] op_sel_hi:[1,0,1] neg_lo:[1,0,0] neg_hi:[1,0,0]
	v_rcp_f32_e32 v138, v138
	v_rcp_f32_e32 v139, v139
	v_rcp_f32_e32 v140, v136
	v_rcp_f32_e32 v141, v137
	v_pk_fma_f32 v[136:137], v[206:207], v[206:207], 1.0 op_sel_hi:[1,1,0] neg_lo:[1,0,0] neg_hi:[1,0,0]
	v_rcp_f32_e32 v134, v134
	v_rcp_f32_e32 v135, v135
	v_exp_f32_e32 v124, v124
	v_exp_f32_e32 v125, v125
	v_sqrt_f32_e32 v220, v136
	v_sqrt_f32_e32 v221, v137
	v_pk_fma_f32 v[126:127], v[126:127], s[36:37], v[94:95] op_sel_hi:[1,0,1] neg_lo:[1,0,0] neg_hi:[1,0,0]
	v_pk_mul_f32 v[142:143], v[90:91], v[142:143]
	v_pk_add_f32 v[132:133], v[132:133], 1.0 op_sel_hi:[1,0]
	v_exp_f32_e32 v126, v126
	v_exp_f32_e32 v127, v127
	v_lshlrev_b32_e32 v202, 16, v186
	v_and_b32_e32 v203, 0xffff0000, v186
	v_lshlrev_b32_e32 v186, 16, v187
	v_and_b32_e32 v187, 0xffff0000, v187
	v_exp_f32_e32 v204, v142
	v_exp_f32_e32 v205, v143
	v_pk_fma_f32 v[130:131], v[130:131], s[36:37], v[86:87] op_sel_hi:[1,0,1] neg_lo:[1,0,0] neg_hi:[1,0,0]
	v_rcp_f32_e32 v132, v132
	v_rcp_f32_e32 v133, v133
	v_pk_mul_f32 v[136:137], v[138:139], v[186:187]
	v_pk_mul_f32 v[138:139], v[140:141], v[202:203]
	v_exp_f32_e32 v130, v130
	v_exp_f32_e32 v131, v131
	v_pk_mul_f32 v[134:135], v[90:91], v[134:135]
	v_pk_add_f32 v[124:125], v[124:125], 1.0 op_sel_hi:[1,0]
	v_pk_mul_f32 v[138:139], v[138:139], v[220:221]
	v_exp_f32_e32 v220, v134
	v_exp_f32_e32 v221, v135
	v_rcp_f32_e32 v124, v124
	v_rcp_f32_e32 v125, v125
	v_pk_fma_f32 v[128:129], v[128:129], s[36:37], v[84:85] op_sel_hi:[1,0,1] neg_lo:[1,0,0] neg_hi:[1,0,0]
	v_pk_add_f32 v[126:127], v[126:127], 1.0 op_sel_hi:[1,0]
	v_pk_fma_f32 v[142:143], v[204:205], v[204:205], 1.0 op_sel_hi:[1,1,0] neg_lo:[1,0,0] neg_hi:[1,0,0]
	v_exp_f32_e32 v128, v128
	v_exp_f32_e32 v129, v129
	v_pk_mul_f32 v[132:133], v[88:89], v[132:133]
	v_rcp_f32_e32 v126, v126
	v_rcp_f32_e32 v127, v127
	v_sqrt_f32_e32 v142, v142
	v_sqrt_f32_e32 v143, v143
	v_pk_add_f32 v[130:131], v[130:131], 1.0 op_sel_hi:[1,0]
	v_exp_f32_e32 v224, v132
	v_exp_f32_e32 v225, v133
	v_pk_fma_f32 v[120:121], v[120:121], s[36:37], v[84:85] op_sel_hi:[1,0,1] neg_lo:[1,0,0] neg_hi:[1,0,0]
	v_rcp_f32_e32 v130, v130
	v_rcp_f32_e32 v131, v131
	v_pk_fma_f32 v[134:135], v[220:221], v[220:221], 1.0 op_sel_hi:[1,1,0] neg_lo:[1,0,0] neg_hi:[1,0,0]
	v_exp_f32_e32 v120, v120
	v_exp_f32_e32 v121, v121
	v_pk_mul_f32 v[124:125], v[88:89], v[124:125]
	v_sqrt_f32_e32 v134, v134
	v_sqrt_f32_e32 v135, v135
	v_pk_fma_f32 v[122:123], v[122:123], s[36:37], v[86:87] op_sel_hi:[1,0,1] neg_lo:[1,0,0] neg_hi:[1,0,0]
	v_exp_f32_e32 v124, v124
	v_exp_f32_e32 v125, v125
	v_pk_add_f32 v[128:129], v[128:129], 1.0 op_sel_hi:[1,0]
	v_exp_f32_e32 v122, v122
	v_exp_f32_e32 v123, v123
	v_pk_mul_f32 v[126:127], v[90:91], v[126:127]
	v_pk_mul_f32 v[136:137], v[136:137], v[142:143]
	v_lshlrev_b32_e32 v142, 16, v185
	v_and_b32_e32 v143, 0xffff0000, v185
	v_rcp_f32_e32 v132, v128
	v_rcp_f32_e32 v133, v129
	v_pk_fma_f32 v[128:129], v[224:225], v[224:225], 1.0 op_sel_hi:[1,1,0] neg_lo:[1,0,0] neg_hi:[1,0,0]
	v_exp_f32_e32 v126, v126
	v_exp_f32_e32 v127, v127
	v_lshlrev_b32_e32 v140, 16, v184
	v_and_b32_e32 v141, 0xffff0000, v184
	v_sqrt_f32_e32 v184, v128
	v_sqrt_f32_e32 v185, v129
	v_pk_mul_f32 v[128:129], v[130:131], v[142:143]
	v_pk_add_f32 v[120:121], v[120:121], 1.0 op_sel_hi:[1,0]
	v_pk_mul_f32 v[128:129], v[128:129], v[134:135]
	v_rcp_f32_e32 v120, v120
	v_rcp_f32_e32 v121, v121
	v_pk_fma_f32 v[134:135], v[124:125], v[124:125], 1.0 op_sel_hi:[1,1,0] neg_lo:[1,0,0] neg_hi:[1,0,0]
	v_pk_add_f32 v[122:123], v[122:123], 1.0 op_sel_hi:[1,0]
	v_sqrt_f32_e32 v134, v134
	v_sqrt_f32_e32 v135, v135
	v_pk_mul_f32 v[130:131], v[132:133], v[140:141]
	v_rcp_f32_e32 v122, v122
	v_rcp_f32_e32 v123, v123
	v_pk_fma_f32 v[132:133], v[126:127], v[126:127], 1.0 op_sel_hi:[1,1,0] neg_lo:[1,0,0] neg_hi:[1,0,0]
	v_pk_mul_f32 v[130:131], v[130:131], v[184:185]
	v_lshlrev_b32_e32 v184, 16, v182
	v_and_b32_e32 v185, 0xffff0000, v182
	v_sqrt_f32_e32 v132, v132
	v_sqrt_f32_e32 v133, v133
	v_mov_b32_e32 v219, v144
	v_pk_mul_f32 v[120:121], v[120:121], v[184:185]
	s_nop 1
v_fmac_f32_dpp v150, v150, v219 row_shr:1 row_mask:0xf bank_mask:0xf
v_fmac_f32_dpp v151, v151, v145 row_shr:1 row_mask:0xf bank_mask:0xf
v_fmac_f32_dpp v148, v148, v146 row_shr:1 row_mask:0xf bank_mask:0xf
v_fmac_f32_dpp v149, v149, v147 row_shr:1 row_mask:0xf bank_mask:0xf
v_mul_f32_dpp v219, v219, v219 row_shr:1 row_mask:0xf bank_mask:0xf
v_mul_f32_dpp v145, v145, v145 row_shr:1 row_mask:0xf bank_mask:0xf
v_mul_f32_dpp v146, v146, v146 row_shr:1 row_mask:0xf bank_mask:0xf
v_mul_f32_dpp v147, v147, v147 row_shr:1 row_mask:0xf bank_mask:0xf
v_fmac_f32_dpp v150, v150, v219 row_shr:2 row_mask:0xf bank_mask:0xf
v_fmac_f32_dpp v151, v151, v145 row_shr:2 row_mask:0xf bank_mask:0xf
v_fmac_f32_dpp v148, v148, v146 row_shr:2 row_mask:0xf bank_mask:0xf
v_fmac_f32_dpp v149, v149, v147 row_shr:2 row_mask:0xf bank_mask:0xf
v_mul_f32_dpp v219, v219, v219 row_shr:2 row_mask:0xf bank_mask:0xf
v_mul_f32_dpp v145, v145, v145 row_shr:2 row_mask:0xf bank_mask:0xf
v_mul_f32_dpp v146, v146, v146 row_shr:2 row_mask:0xf bank_mask:0xf
v_mul_f32_dpp v147, v147, v147 row_shr:2 row_mask:0xf bank_mask:0xf
v_fmac_f32_dpp v150, v150, v219 row_shr:4 row_mask:0xf bank_mask:0xf
v_fmac_f32_dpp v151, v151, v145 row_shr:4 row_mask:0xf bank_mask:0xf
v_fmac_f32_dpp v148, v148, v146 row_shr:4 row_mask:0xf bank_mask:0xf
v_fmac_f32_dpp v149, v149, v147 row_shr:4 row_mask:0xf bank_mask:0xf
v_mul_f32_dpp v219, v219, v219 row_shr:4 row_mask:0xf bank_mask:0xf
v_mul_f32_dpp v145, v145, v145 row_shr:4 row_mask:0xf bank_mask:0xf
v_mul_f32_dpp v146, v146, v146 row_shr:4 row_mask:0xf bank_mask:0xf
v_mul_f32_dpp v147, v147, v147 row_shr:4 row_mask:0xf bank_mask:0xf
v_fmac_f32_dpp v150, v150, v219 row_shr:8 row_mask:0xf bank_mask:0xf
v_fmac_f32_dpp v151, v151, v145 row_shr:8 row_mask:0xf bank_mask:0xf
v_fmac_f32_dpp v148, v148, v146 row_shr:8 row_mask:0xf bank_mask:0xf
v_fmac_f32_dpp v149, v149, v147 row_shr:8 row_mask:0xf bank_mask:0xf
v_mul_f32_dpp v219, v219, v219 row_shr:8 row_mask:0xf bank_mask:0xf
v_mul_f32_dpp v145, v145, v145 row_shr:8 row_mask:0xf bank_mask:0xf
v_mul_f32_dpp v146, v146, v146 row_shr:8 row_mask:0xf bank_mask:0xf
v_mul_f32_dpp v147, v147, v147 row_shr:8 row_mask:0xf bank_mask:0xf

	v_lshlrev_b32_e32 v182, 16, v183
	v_and_b32_e32 v183, 0xffff0000, v183
	v_pk_mul_f32 v[134:135], v[120:121], v[134:135]
	v_and_or_b32 v121, v214, 64, v223
	v_pk_mul_f32 v[122:123], v[122:123], v[182:183]
	v_lshlrev_b32_e32 v144, 2, v121
	v_fmac_f32_e32 v150, 0, v219
	v_fmac_f32_e32 v151, 0, v145
	v_fmac_f32_e32 v148, 0, v146
	v_fmac_f32_e32 v149, 0, v147
	v_pk_mul_f32 v[132:133], v[122:123], v[132:133]
	v_mov_b32_e32 v120, v124
	v_mov_b32_e32 v124, v126
	ds_bpermute_b32 v121, v144, v150 offset:60
	ds_bpermute_b32 v122, v144, v219 offset:60
	ds_bpermute_b32 v123, v144, v151 offset:60
	ds_bpermute_b32 v126, v144, v145 offset:60
	ds_bpermute_b32 v223, v144, v148 offset:60
	ds_bpermute_b32 v227, v144, v146 offset:60
	ds_bpermute_b32 v228, v144, v149 offset:60
	ds_bpermute_b32 v230, v144, v147 offset:60
	s_nop 1
v_fmac_f32_dpp v138, v138, v206 row_shr:1 row_mask:0xf bank_mask:0xf
v_fmac_f32_dpp v139, v139, v207 row_shr:1 row_mask:0xf bank_mask:0xf
v_fmac_f32_dpp v136, v136, v204 row_shr:1 row_mask:0xf bank_mask:0xf
v_fmac_f32_dpp v137, v137, v205 row_shr:1 row_mask:0xf bank_mask:0xf
v_mul_f32_dpp v206, v206, v206 row_shr:1 row_mask:0xf bank_mask:0xf
v_mul_f32_dpp v207, v207, v207 row_shr:1 row_mask:0xf bank_mask:0xf
v_mul_f32_dpp v204, v204, v204 row_shr:1 row_mask:0xf bank_mask:0xf
v_mul_f32_dpp v205, v205, v205 row_shr:1 row_mask:0xf bank_mask:0xf
v_fmac_f32_dpp v138, v138, v206 row_shr:2 row_mask:0xf bank_mask:0xf
v_fmac_f32_dpp v139, v139, v207 row_shr:2 row_mask:0xf bank_mask:0xf
v_fmac_f32_dpp v136, v136, v204 row_shr:2 row_mask:0xf bank_mask:0xf
v_fmac_f32_dpp v137, v137, v205 row_shr:2 row_mask:0xf bank_mask:0xf
v_mul_f32_dpp v206, v206, v206 row_shr:2 row_mask:0xf bank_mask:0xf
v_mul_f32_dpp v207, v207, v207 row_shr:2 row_mask:0xf bank_mask:0xf
v_mul_f32_dpp v204, v204, v204 row_shr:2 row_mask:0xf bank_mask:0xf
v_mul_f32_dpp v205, v205, v205 row_shr:2 row_mask:0xf bank_mask:0xf
v_fmac_f32_dpp v138, v138, v206 row_shr:4 row_mask:0xf bank_mask:0xf
v_fmac_f32_dpp v139, v139, v207 row_shr:4 row_mask:0xf bank_mask:0xf
v_fmac_f32_dpp v136, v136, v204 row_shr:4 row_mask:0xf bank_mask:0xf
v_fmac_f32_dpp v137, v137, v205 row_shr:4 row_mask:0xf bank_mask:0xf
v_mul_f32_dpp v206, v206, v206 row_shr:4 row_mask:0xf bank_mask:0xf
v_mul_f32_dpp v207, v207, v207 row_shr:4 row_mask:0xf bank_mask:0xf
v_mul_f32_dpp v204, v204, v204 row_shr:4 row_mask:0xf bank_mask:0xf
v_mul_f32_dpp v205, v205, v205 row_shr:4 row_mask:0xf bank_mask:0xf
v_fmac_f32_dpp v138, v138, v206 row_shr:8 row_mask:0xf bank_mask:0xf
v_fmac_f32_dpp v139, v139, v207 row_shr:8 row_mask:0xf bank_mask:0xf
v_fmac_f32_dpp v136, v136, v204 row_shr:8 row_mask:0xf bank_mask:0xf
v_fmac_f32_dpp v137, v137, v205 row_shr:8 row_mask:0xf bank_mask:0xf
v_mul_f32_dpp v206, v206, v206 row_shr:8 row_mask:0xf bank_mask:0xf
v_mul_f32_dpp v207, v207, v207 row_shr:8 row_mask:0xf bank_mask:0xf
v_mul_f32_dpp v204, v204, v204 row_shr:8 row_mask:0xf bank_mask:0xf
v_mul_f32_dpp v205, v205, v205 row_shr:8 row_mask:0xf bank_mask:0xf

	v_mov_b32_e32 v229, v220
	v_mov_b32_e32 v220, v225
	s_waitcnt lgkmcnt(7)
	v_fmac_f32_e32 v138, v206, v121
	s_waitcnt lgkmcnt(6)
	v_mul_f32_e32 v225, v206, v122
	s_waitcnt lgkmcnt(5)
	v_fmac_f32_e32 v139, v207, v123
	s_waitcnt lgkmcnt(4)
	v_mul_f32_e32 v226, v207, v126
	s_waitcnt lgkmcnt(3)
	v_fmac_f32_e32 v136, v204, v223
	s_waitcnt lgkmcnt(2)
	v_mul_f32_e32 v227, v204, v227
	s_waitcnt lgkmcnt(1)
	v_fmac_f32_e32 v137, v205, v228
	s_waitcnt lgkmcnt(0)
	v_mul_f32_e32 v228, v205, v230
	ds_bpermute_b32 v121, v144, v138 offset:60
	ds_bpermute_b32 v122, v144, v225 offset:60
	ds_bpermute_b32 v123, v144, v139 offset:60
	ds_bpermute_b32 v126, v144, v226 offset:60
	ds_bpermute_b32 v204, v144, v136 offset:60
	ds_bpermute_b32 v207, v144, v227 offset:60
	ds_bpermute_b32 v205, v144, v137 offset:60
	ds_bpermute_b32 v230, v144, v228 offset:60
	s_nop 1
v_fmac_f32_dpp v130, v130, v224 row_shr:1 row_mask:0xf bank_mask:0xf
v_fmac_f32_dpp v131, v131, v220 row_shr:1 row_mask:0xf bank_mask:0xf
v_fmac_f32_dpp v128, v128, v229 row_shr:1 row_mask:0xf bank_mask:0xf
v_fmac_f32_dpp v129, v129, v221 row_shr:1 row_mask:0xf bank_mask:0xf
v_mul_f32_dpp v224, v224, v224 row_shr:1 row_mask:0xf bank_mask:0xf
v_mul_f32_dpp v220, v220, v220 row_shr:1 row_mask:0xf bank_mask:0xf
v_mul_f32_dpp v229, v229, v229 row_shr:1 row_mask:0xf bank_mask:0xf
v_mul_f32_dpp v221, v221, v221 row_shr:1 row_mask:0xf bank_mask:0xf
v_fmac_f32_dpp v130, v130, v224 row_shr:2 row_mask:0xf bank_mask:0xf
v_fmac_f32_dpp v131, v131, v220 row_shr:2 row_mask:0xf bank_mask:0xf
v_fmac_f32_dpp v128, v128, v229 row_shr:2 row_mask:0xf bank_mask:0xf
v_fmac_f32_dpp v129, v129, v221 row_shr:2 row_mask:0xf bank_mask:0xf
v_mul_f32_dpp v224, v224, v224 row_shr:2 row_mask:0xf bank_mask:0xf
v_mul_f32_dpp v220, v220, v220 row_shr:2 row_mask:0xf bank_mask:0xf
v_mul_f32_dpp v229, v229, v229 row_shr:2 row_mask:0xf bank_mask:0xf
v_mul_f32_dpp v221, v221, v221 row_shr:2 row_mask:0xf bank_mask:0xf
v_fmac_f32_dpp v130, v130, v224 row_shr:4 row_mask:0xf bank_mask:0xf
v_fmac_f32_dpp v131, v131, v220 row_shr:4 row_mask:0xf bank_mask:0xf
v_fmac_f32_dpp v128, v128, v229 row_shr:4 row_mask:0xf bank_mask:0xf
v_fmac_f32_dpp v129, v129, v221 row_shr:4 row_mask:0xf bank_mask:0xf
v_mul_f32_dpp v224, v224, v224 row_shr:4 row_mask:0xf bank_mask:0xf
v_mul_f32_dpp v220, v220, v220 row_shr:4 row_mask:0xf bank_mask:0xf
v_mul_f32_dpp v229, v229, v229 row_shr:4 row_mask:0xf bank_mask:0xf
v_mul_f32_dpp v221, v221, v221 row_shr:4 row_mask:0xf bank_mask:0xf
v_fmac_f32_dpp v130, v130, v224 row_shr:8 row_mask:0xf bank_mask:0xf
v_fmac_f32_dpp v131, v131, v220 row_shr:8 row_mask:0xf bank_mask:0xf
v_fmac_f32_dpp v128, v128, v229 row_shr:8 row_mask:0xf bank_mask:0xf
v_fmac_f32_dpp v129, v129, v221 row_shr:8 row_mask:0xf bank_mask:0xf
v_mul_f32_dpp v224, v224, v224 row_shr:8 row_mask:0xf bank_mask:0xf
v_mul_f32_dpp v220, v220, v220 row_shr:8 row_mask:0xf bank_mask:0xf
v_mul_f32_dpp v229, v229, v229 row_shr:8 row_mask:0xf bank_mask:0xf
v_mul_f32_dpp v221, v221, v221 row_shr:8 row_mask:0xf bank_mask:0xf

	s_ashr_i32 s8, s90, 5
	s_waitcnt lgkmcnt(7)
	v_fmac_f32_e32 v130, v224, v121
	s_waitcnt lgkmcnt(6)
	v_mul_f32_e32 v206, v224, v122
	s_waitcnt lgkmcnt(5)
	v_fmac_f32_e32 v131, v220, v123
	s_waitcnt lgkmcnt(4)
	v_mul_f32_e32 v220, v220, v126
	s_waitcnt lgkmcnt(3)
	v_fmac_f32_e32 v128, v229, v204
	s_waitcnt lgkmcnt(2)
	v_mul_f32_e32 v223, v229, v207
	s_waitcnt lgkmcnt(1)
	v_fmac_f32_e32 v129, v221, v205
	s_waitcnt lgkmcnt(0)
	v_mul_f32_e32 v224, v221, v230
	ds_bpermute_b32 v121, v144, v130 offset:60
	ds_bpermute_b32 v122, v144, v206 offset:60
	ds_bpermute_b32 v123, v144, v131 offset:60
	ds_bpermute_b32 v126, v144, v220 offset:60
	ds_bpermute_b32 v207, v144, v128 offset:60
	ds_bpermute_b32 v229, v144, v223 offset:60
	ds_bpermute_b32 v221, v144, v129 offset:60
	ds_bpermute_b32 v230, v144, v224 offset:60
	s_add_i32 s9, s90, 0xffffff00
	s_and_b64 s[4:5], exec, s[54:55]
	s_cselect_b32 s4, s9, s8
	s_nop 1
v_fmac_f32_dpp v134, v134, v120 row_shr:1 row_mask:0xf bank_mask:0xf
v_fmac_f32_dpp v135, v135, v125 row_shr:1 row_mask:0xf bank_mask:0xf
v_fmac_f32_dpp v132, v132, v124 row_shr:1 row_mask:0xf bank_mask:0xf
v_fmac_f32_dpp v133, v133, v127 row_shr:1 row_mask:0xf bank_mask:0xf
v_mul_f32_dpp v120, v120, v120 row_shr:1 row_mask:0xf bank_mask:0xf
v_mul_f32_dpp v125, v125, v125 row_shr:1 row_mask:0xf bank_mask:0xf
v_mul_f32_dpp v124, v124, v124 row_shr:1 row_mask:0xf bank_mask:0xf
v_mul_f32_dpp v127, v127, v127 row_shr:1 row_mask:0xf bank_mask:0xf
v_fmac_f32_dpp v134, v134, v120 row_shr:2 row_mask:0xf bank_mask:0xf
v_fmac_f32_dpp v135, v135, v125 row_shr:2 row_mask:0xf bank_mask:0xf
v_fmac_f32_dpp v132, v132, v124 row_shr:2 row_mask:0xf bank_mask:0xf
v_fmac_f32_dpp v133, v133, v127 row_shr:2 row_mask:0xf bank_mask:0xf
v_mul_f32_dpp v120, v120, v120 row_shr:2 row_mask:0xf bank_mask:0xf
v_mul_f32_dpp v125, v125, v125 row_shr:2 row_mask:0xf bank_mask:0xf
v_mul_f32_dpp v124, v124, v124 row_shr:2 row_mask:0xf bank_mask:0xf
v_mul_f32_dpp v127, v127, v127 row_shr:2 row_mask:0xf bank_mask:0xf
v_fmac_f32_dpp v134, v134, v120 row_shr:4 row_mask:0xf bank_mask:0xf
v_fmac_f32_dpp v135, v135, v125 row_shr:4 row_mask:0xf bank_mask:0xf
v_fmac_f32_dpp v132, v132, v124 row_shr:4 row_mask:0xf bank_mask:0xf
v_fmac_f32_dpp v133, v133, v127 row_shr:4 row_mask:0xf bank_mask:0xf
v_mul_f32_dpp v120, v120, v120 row_shr:4 row_mask:0xf bank_mask:0xf
v_mul_f32_dpp v125, v125, v125 row_shr:4 row_mask:0xf bank_mask:0xf
v_mul_f32_dpp v124, v124, v124 row_shr:4 row_mask:0xf bank_mask:0xf
v_mul_f32_dpp v127, v127, v127 row_shr:4 row_mask:0xf bank_mask:0xf
v_fmac_f32_dpp v134, v134, v120 row_shr:8 row_mask:0xf bank_mask:0xf
v_fmac_f32_dpp v135, v135, v125 row_shr:8 row_mask:0xf bank_mask:0xf
v_fmac_f32_dpp v132, v132, v124 row_shr:8 row_mask:0xf bank_mask:0xf
v_fmac_f32_dpp v133, v133, v127 row_shr:8 row_mask:0xf bank_mask:0xf
v_mul_f32_dpp v120, v120, v120 row_shr:8 row_mask:0xf bank_mask:0xf
v_mul_f32_dpp v125, v125, v125 row_shr:8 row_mask:0xf bank_mask:0xf
v_mul_f32_dpp v124, v124, v124 row_shr:8 row_mask:0xf bank_mask:0xf
v_mul_f32_dpp v127, v127, v127 row_shr:8 row_mask:0xf bank_mask:0xf

	s_lshl_b32 s47, s4, 1
	s_lshl_b32 s4, s90, 2
	s_waitcnt lgkmcnt(7)
	v_fmac_f32_e32 v134, v120, v121
	s_waitcnt lgkmcnt(6)
	v_mul_f32_e32 v204, v120, v122
	s_waitcnt lgkmcnt(5)
	v_fmac_f32_e32 v135, v125, v123
	s_waitcnt lgkmcnt(4)
	v_mul_f32_e32 v205, v125, v126
	s_waitcnt lgkmcnt(3)
	v_fmac_f32_e32 v132, v124, v207
	s_waitcnt lgkmcnt(2)
	v_mul_f32_e32 v207, v124, v229
	s_waitcnt lgkmcnt(1)
	v_fmac_f32_e32 v133, v127, v221
	s_waitcnt lgkmcnt(0)
	v_mul_f32_e32 v221, v127, v230
	s_and_b32 s49, s4, 0x7c
	v_mov_b32_e32 v121, v134
	v_mov_b32_e32 v120, v204
	v_mov_b32_e32 v123, v135
	v_mov_b32_e32 v122, v205
	v_mov_b32_e32 v125, v132
	v_mov_b32_e32 v124, v207
	v_mov_b32_e32 v127, v133
	v_mov_b32_e32 v126, v221
	s_add_i32 s8, s49, 4
	s_and_b64 s[4:5], exec, s[54:55]
	s_cselect_b32 s14, 0, s8
	s_add_i32 s14, s14, s66
	v_cmp_eq_u32_e64 s[10:11], 15, v215
	s_mul_hi_i32 s58, s47, 0x84
	s_mul_i32 s59, s47, 0x84
	s_and_saveexec_b64 s[8:9], s[10:11]
	s_cbranch_execz .LBB0_437
	s_add_u32 s4, s59, s14
	s_addc_u32 s5, s58, 0
	s_mulk_i32 s5, 0x2800
	s_mul_hi_u32 s12, s4, 0x2800
	s_add_i32 s12, s12, s5
	s_mulk_i32 s4, 0x2800
	s_add_u32 s4, s77, s4
	s_addc_u32 s5, s78, s12
	v_lshl_add_u64 v[230:231], v[176:177], 3, s[4:5]
	s_waitcnt lgkmcnt(4)
	flat_store_dwordx4 v[230:231], v[120:123]
	s_waitcnt lgkmcnt(0)
	flat_store_dwordx4 v[230:231], v[124:127] offset:16
.LBB0_437:
	s_or_b64 exec, exec, s[8:9]
	v_pk_fma_f32 v[116:117], v[116:117], s[36:37], v[72:73] op_sel_hi:[1,0,1] neg_lo:[1,0,0] neg_hi:[1,0,0]
	v_pk_fma_f32 v[108:109], v[108:109], s[36:37], v[72:73] op_sel_hi:[1,0,1] neg_lo:[1,0,0] neg_hi:[1,0,0]
	v_exp_f32_e32 v116, v116
	v_exp_f32_e32 v117, v117
	v_pk_fma_f32 v[114:115], v[114:115], s[36:37], v[70:71] op_sel_hi:[1,0,1] neg_lo:[1,0,0] neg_hi:[1,0,0]
	v_pk_fma_f32 v[112:113], v[112:113], s[36:37], v[68:69] op_sel_hi:[1,0,1] neg_lo:[1,0,0] neg_hi:[1,0,0]
	v_exp_f32_e32 v108, v108
	v_pk_add_f32 v[116:117], v[116:117], 1.0 op_sel_hi:[1,0]
	v_exp_f32_e32 v109, v109
	v_rcp_f32_e32 v116, v116
	v_rcp_f32_e32 v117, v117
	v_exp_f32_e32 v114, v114
	v_exp_f32_e32 v115, v115
	v_exp_f32_e32 v112, v112
	v_exp_f32_e32 v113, v113
	v_pk_mul_f32 v[116:117], v[64:65], v[116:117]
	v_pk_add_f32 v[108:109], v[108:109], 1.0 op_sel_hi:[1,0]
	v_pk_add_f32 v[114:115], v[114:115], 1.0 op_sel_hi:[1,0]
	v_exp_f32_e32 v116, v116
	v_exp_f32_e32 v117, v117
	v_pk_add_f32 v[112:113], v[112:113], 1.0 op_sel_hi:[1,0]
	v_rcp_f32_e32 v108, v108
	v_rcp_f32_e32 v109, v109
	v_rcp_f32_e32 v114, v114
	v_rcp_f32_e32 v115, v115
	s_waitcnt lgkmcnt(0)
	v_rcp_f32_e32 v122, v112
	v_rcp_f32_e32 v123, v113
	v_pk_fma_f32 v[106:107], v[106:107], s[36:37], v[70:71] op_sel_hi:[1,0,1] neg_lo:[1,0,0] neg_hi:[1,0,0]
	v_pk_fma_f32 v[104:105], v[104:105], s[36:37], v[68:69] op_sel_hi:[1,0,1] neg_lo:[1,0,0] neg_hi:[1,0,0]
	v_pk_fma_f32 v[102:103], v[102:103], s[36:37], v[74:75] op_sel_hi:[1,0,1] neg_lo:[1,0,0] neg_hi:[1,0,0]
	v_pk_fma_f32 v[112:113], v[116:117], v[116:117], 1.0 op_sel_hi:[1,1,0] neg_lo:[1,0,0] neg_hi:[1,0,0]
	v_exp_f32_e32 v106, v106
	v_exp_f32_e32 v107, v107
	v_exp_f32_e32 v104, v104
	v_exp_f32_e32 v105, v105
	v_pk_mul_f32 v[108:109], v[64:65], v[108:109]
	v_exp_f32_e32 v102, v102
	v_exp_f32_e32 v103, v103
	v_sqrt_f32_e32 v124, v112
	v_sqrt_f32_e32 v125, v113
	v_pk_mul_f32 v[112:113], v[114:115], v[188:189]
	v_pk_mul_f32 v[114:115], v[122:123], v[200:201]
	v_exp_f32_e32 v122, v108
	v_exp_f32_e32 v123, v109
	v_pk_fma_f32 v[100:101], v[100:101], s[36:37], v[72:73] op_sel_hi:[1,0,1] neg_lo:[1,0,0] neg_hi:[1,0,0]
	v_pk_fma_f32 v[118:119], v[118:119], s[36:37], v[74:75] op_sel_hi:[1,0,1] neg_lo:[1,0,0] neg_hi:[1,0,0]
	v_exp_f32_e32 v100, v100
	v_exp_f32_e32 v101, v101
	v_exp_f32_e32 v118, v118
	v_exp_f32_e32 v119, v119
	v_pk_add_f32 v[106:107], v[106:107], 1.0 op_sel_hi:[1,0]
	v_pk_add_f32 v[104:105], v[104:105], 1.0 op_sel_hi:[1,0]
	v_pk_add_f32 v[102:103], v[102:103], 1.0 op_sel_hi:[1,0]
	v_rcp_f32_e32 v106, v106
	v_rcp_f32_e32 v107, v107
	v_rcp_f32_e32 v108, v104
	v_rcp_f32_e32 v109, v105
	v_pk_fma_f32 v[104:105], v[122:123], v[122:123], 1.0 op_sel_hi:[1,1,0] neg_lo:[1,0,0] neg_hi:[1,0,0]
	v_rcp_f32_e32 v102, v102
	v_rcp_f32_e32 v103, v103
	v_pk_mul_f32 v[114:115], v[114:115], v[124:125]
	v_sqrt_f32_e32 v124, v104
	v_sqrt_f32_e32 v125, v105
	v_pk_add_f32 v[100:101], v[100:101], 1.0 op_sel_hi:[1,0]
	v_pk_add_f32 v[118:119], v[118:119], 1.0 op_sel_hi:[1,0]
	v_pk_fma_f32 v[110:111], v[110:111], s[36:37], v[74:75] op_sel_hi:[1,0,1] neg_lo:[1,0,0] neg_hi:[1,0,0]
	v_pk_fma_f32 v[98:99], v[98:99], s[36:37], v[70:71] op_sel_hi:[1,0,1] neg_lo:[1,0,0] neg_hi:[1,0,0]
	v_rcp_f32_e32 v100, v100
	v_rcp_f32_e32 v101, v101
	v_pk_fma_f32 v[82:83], v[82:83], s[36:37], v[74:75] op_sel_hi:[1,0,1] neg_lo:[1,0,0] neg_hi:[1,0,0]
	v_pk_fma_f32 v[80:81], v[80:81], s[36:37], v[72:73] op_sel_hi:[1,0,1] neg_lo:[1,0,0] neg_hi:[1,0,0]
	v_rcp_f32_e32 v118, v118
	v_rcp_f32_e32 v119, v119
	v_exp_f32_e32 v110, v110
	v_exp_f32_e32 v111, v111
	v_pk_mul_f32 v[104:105], v[106:107], v[186:187]
	v_pk_mul_f32 v[106:107], v[108:109], v[202:203]
	v_exp_f32_e32 v98, v98
	v_exp_f32_e32 v99, v99
	v_pk_mul_f32 v[102:103], v[66:67], v[102:103]
	v_pk_fma_f32 v[96:97], v[96:97], s[36:37], v[68:69] op_sel_hi:[1,0,1] neg_lo:[1,0,0] neg_hi:[1,0,0]
	v_exp_f32_e32 v82, v82
	v_exp_f32_e32 v83, v83
	v_exp_f32_e32 v80, v80
	v_exp_f32_e32 v81, v81
	v_pk_mul_f32 v[106:107], v[106:107], v[124:125]
	v_exp_f32_e32 v124, v102
	v_exp_f32_e32 v125, v103
	v_exp_f32_e32 v96, v96
	v_exp_f32_e32 v97, v97
	v_pk_mul_f32 v[100:101], v[64:65], v[100:101]
	v_pk_mul_f32 v[118:119], v[66:67], v[118:119]
	v_pk_add_f32 v[110:111], v[110:111], 1.0 op_sel_hi:[1,0]
	v_pk_add_f32 v[98:99], v[98:99], 1.0 op_sel_hi:[1,0]
	v_exp_f32_e32 v126, v100
	v_exp_f32_e32 v127, v101
	v_pk_add_f32 v[82:83], v[82:83], 1.0 op_sel_hi:[1,0]
	v_pk_add_f32 v[80:81], v[80:81], 1.0 op_sel_hi:[1,0]
	v_exp_f32_e32 v118, v118
	v_exp_f32_e32 v119, v119
	v_rcp_f32_e32 v110, v110
	v_rcp_f32_e32 v111, v111
	v_rcp_f32_e32 v98, v98
	v_rcp_f32_e32 v99, v99
	v_pk_fma_f32 v[102:103], v[124:125], v[124:125], 1.0 op_sel_hi:[1,1,0] neg_lo:[1,0,0] neg_hi:[1,0,0]
	v_pk_add_f32 v[96:97], v[96:97], 1.0 op_sel_hi:[1,0]
	v_rcp_f32_e32 v82, v82
	v_rcp_f32_e32 v83, v83
	v_rcp_f32_e32 v80, v80
	v_rcp_f32_e32 v81, v81
	v_sqrt_f32_e32 v102, v102
	v_sqrt_f32_e32 v103, v103
	v_rcp_f32_e32 v100, v96
	v_rcp_f32_e32 v101, v97
	v_pk_fma_f32 v[96:97], v[126:127], v[126:127], 1.0 op_sel_hi:[1,1,0] neg_lo:[1,0,0] neg_hi:[1,0,0]
	v_pk_fma_f32 v[78:79], v[78:79], s[36:37], v[70:71] op_sel_hi:[1,0,1] neg_lo:[1,0,0] neg_hi:[1,0,0]
	v_pk_fma_f32 v[76:77], v[76:77], s[36:37], v[68:69] op_sel_hi:[1,0,1] neg_lo:[1,0,0] neg_hi:[1,0,0]
	v_pk_fma_f32 v[120:121], v[118:119], v[118:119], 1.0 op_sel_hi:[1,1,0] neg_lo:[1,0,0] neg_hi:[1,0,0]
	v_pk_mul_f32 v[110:111], v[66:67], v[110:111]
	v_sqrt_f32_e32 v108, v96
	v_sqrt_f32_e32 v109, v97
	v_pk_mul_f32 v[96:97], v[98:99], v[142:143]
	v_exp_f32_e32 v78, v78
	v_exp_f32_e32 v79, v79
	v_pk_mul_f32 v[82:83], v[66:67], v[82:83]
	v_exp_f32_e32 v76, v76
	v_exp_f32_e32 v77, v77
	v_pk_mul_f32 v[80:81], v[64:65], v[80:81]
	v_sqrt_f32_e32 v120, v120
	v_sqrt_f32_e32 v121, v121
	v_exp_f32_e32 v110, v110
	v_exp_f32_e32 v111, v111
	v_pk_mul_f32 v[96:97], v[96:97], v[102:103]
	v_pk_mul_f32 v[98:99], v[100:101], v[140:141]
	v_exp_f32_e32 v100, v82
	v_exp_f32_e32 v101, v83
	v_exp_f32_e32 v102, v80
	v_exp_f32_e32 v103, v81
	v_pk_add_f32 v[78:79], v[78:79], 1.0 op_sel_hi:[1,0]
	v_pk_add_f32 v[76:77], v[76:77], 1.0 op_sel_hi:[1,0]
	v_pk_mul_f32 v[112:113], v[112:113], v[120:121]
	v_pk_fma_f32 v[120:121], v[110:111], v[110:111], 1.0 op_sel_hi:[1,1,0] neg_lo:[1,0,0] neg_hi:[1,0,0]
	v_rcp_f32_e32 v78, v78
	v_rcp_f32_e32 v79, v79
	v_pk_fma_f32 v[82:83], v[100:101], v[100:101], 1.0 op_sel_hi:[1,1,0] neg_lo:[1,0,0] neg_hi:[1,0,0]
	v_rcp_f32_e32 v76, v76
	v_rcp_f32_e32 v77, v77
	v_pk_fma_f32 v[80:81], v[102:103], v[102:103], 1.0 op_sel_hi:[1,1,0] neg_lo:[1,0,0] neg_hi:[1,0,0]
	v_sqrt_f32_e32 v120, v120
	v_sqrt_f32_e32 v121, v121
	v_sqrt_f32_e32 v82, v82
	v_sqrt_f32_e32 v83, v83
	v_sqrt_f32_e32 v80, v80
	v_sqrt_f32_e32 v81, v81
	v_pk_mul_f32 v[78:79], v[78:79], v[182:183]
	v_pk_mul_f32 v[76:77], v[76:77], v[184:185]
	v_mov_b32_e32 v188, v118
	v_mov_b32_e32 v189, v117
	v_pk_mul_f32 v[104:105], v[104:105], v[120:121]
	v_mov_b32_e32 v186, v122
	v_pk_mul_f32 v[98:99], v[98:99], v[108:109]
	v_mov_b32_e32 v117, v126
	v_mov_b32_e32 v122, v124
	v_pk_mul_f32 v[108:109], v[78:79], v[82:83]
	v_pk_mul_f32 v[120:121], v[76:77], v[80:81]
	s_nop 1
v_fmac_f32_dpp v114, v114, v116 row_shl:1 row_mask:0xf bank_mask:0xf
v_fmac_f32_dpp v115, v115, v189 row_shl:1 row_mask:0xf bank_mask:0xf
v_fmac_f32_dpp v112, v112, v188 row_shl:1 row_mask:0xf bank_mask:0xf
v_fmac_f32_dpp v113, v113, v119 row_shl:1 row_mask:0xf bank_mask:0xf
v_mul_f32_dpp v116, v116, v116 row_shl:1 row_mask:0xf bank_mask:0xf
v_mul_f32_dpp v189, v189, v189 row_shl:1 row_mask:0xf bank_mask:0xf
v_mul_f32_dpp v188, v188, v188 row_shl:1 row_mask:0xf bank_mask:0xf
v_mul_f32_dpp v119, v119, v119 row_shl:1 row_mask:0xf bank_mask:0xf
v_fmac_f32_dpp v114, v114, v116 row_shl:2 row_mask:0xf bank_mask:0xf
v_fmac_f32_dpp v115, v115, v189 row_shl:2 row_mask:0xf bank_mask:0xf
v_fmac_f32_dpp v112, v112, v188 row_shl:2 row_mask:0xf bank_mask:0xf
v_fmac_f32_dpp v113, v113, v119 row_shl:2 row_mask:0xf bank_mask:0xf
v_mul_f32_dpp v116, v116, v116 row_shl:2 row_mask:0xf bank_mask:0xf
v_mul_f32_dpp v189, v189, v189 row_shl:2 row_mask:0xf bank_mask:0xf
v_mul_f32_dpp v188, v188, v188 row_shl:2 row_mask:0xf bank_mask:0xf
v_mul_f32_dpp v119, v119, v119 row_shl:2 row_mask:0xf bank_mask:0xf
v_fmac_f32_dpp v114, v114, v116 row_shl:4 row_mask:0xf bank_mask:0xf
v_fmac_f32_dpp v115, v115, v189 row_shl:4 row_mask:0xf bank_mask:0xf
v_fmac_f32_dpp v112, v112, v188 row_shl:4 row_mask:0xf bank_mask:0xf
v_fmac_f32_dpp v113, v113, v119 row_shl:4 row_mask:0xf bank_mask:0xf
v_mul_f32_dpp v116, v116, v116 row_shl:4 row_mask:0xf bank_mask:0xf
v_mul_f32_dpp v189, v189, v189 row_shl:4 row_mask:0xf bank_mask:0xf
v_mul_f32_dpp v188, v188, v188 row_shl:4 row_mask:0xf bank_mask:0xf
v_mul_f32_dpp v119, v119, v119 row_shl:4 row_mask:0xf bank_mask:0xf
v_fmac_f32_dpp v114, v114, v116 row_shl:8 row_mask:0xf bank_mask:0xf
v_fmac_f32_dpp v115, v115, v189 row_shl:8 row_mask:0xf bank_mask:0xf
v_fmac_f32_dpp v112, v112, v188 row_shl:8 row_mask:0xf bank_mask:0xf
v_fmac_f32_dpp v113, v113, v119 row_shl:8 row_mask:0xf bank_mask:0xf
v_mul_f32_dpp v116, v116, v116 row_shl:8 row_mask:0xf bank_mask:0xf
v_mul_f32_dpp v189, v189, v189 row_shl:8 row_mask:0xf bank_mask:0xf
v_mul_f32_dpp v188, v188, v188 row_shl:8 row_mask:0xf bank_mask:0xf
v_mul_f32_dpp v119, v119, v119 row_shl:8 row_mask:0xf bank_mask:0xf

	s_nop 1
v_fmac_f32_dpp v106, v106, v186 row_shl:1 row_mask:0xf bank_mask:0xf
v_fmac_f32_dpp v107, v107, v123 row_shl:1 row_mask:0xf bank_mask:0xf
v_fmac_f32_dpp v104, v104, v110 row_shl:1 row_mask:0xf bank_mask:0xf
v_fmac_f32_dpp v105, v105, v111 row_shl:1 row_mask:0xf bank_mask:0xf
v_mul_f32_dpp v186, v186, v186 row_shl:1 row_mask:0xf bank_mask:0xf
v_mul_f32_dpp v123, v123, v123 row_shl:1 row_mask:0xf bank_mask:0xf
v_mul_f32_dpp v110, v110, v110 row_shl:1 row_mask:0xf bank_mask:0xf
v_mul_f32_dpp v111, v111, v111 row_shl:1 row_mask:0xf bank_mask:0xf
v_fmac_f32_dpp v106, v106, v186 row_shl:2 row_mask:0xf bank_mask:0xf
v_fmac_f32_dpp v107, v107, v123 row_shl:2 row_mask:0xf bank_mask:0xf
v_fmac_f32_dpp v104, v104, v110 row_shl:2 row_mask:0xf bank_mask:0xf
v_fmac_f32_dpp v105, v105, v111 row_shl:2 row_mask:0xf bank_mask:0xf
v_mul_f32_dpp v186, v186, v186 row_shl:2 row_mask:0xf bank_mask:0xf
v_mul_f32_dpp v123, v123, v123 row_shl:2 row_mask:0xf bank_mask:0xf
v_mul_f32_dpp v110, v110, v110 row_shl:2 row_mask:0xf bank_mask:0xf
v_mul_f32_dpp v111, v111, v111 row_shl:2 row_mask:0xf bank_mask:0xf
v_fmac_f32_dpp v106, v106, v186 row_shl:4 row_mask:0xf bank_mask:0xf
v_fmac_f32_dpp v107, v107, v123 row_shl:4 row_mask:0xf bank_mask:0xf
v_fmac_f32_dpp v104, v104, v110 row_shl:4 row_mask:0xf bank_mask:0xf
v_fmac_f32_dpp v105, v105, v111 row_shl:4 row_mask:0xf bank_mask:0xf
v_mul_f32_dpp v186, v186, v186 row_shl:4 row_mask:0xf bank_mask:0xf
v_mul_f32_dpp v123, v123, v123 row_shl:4 row_mask:0xf bank_mask:0xf
v_mul_f32_dpp v110, v110, v110 row_shl:4 row_mask:0xf bank_mask:0xf
v_mul_f32_dpp v111, v111, v111 row_shl:4 row_mask:0xf bank_mask:0xf
v_fmac_f32_dpp v106, v106, v186 row_shl:8 row_mask:0xf bank_mask:0xf
v_fmac_f32_dpp v107, v107, v123 row_shl:8 row_mask:0xf bank_mask:0xf
v_fmac_f32_dpp v104, v104, v110 row_shl:8 row_mask:0xf bank_mask:0xf
v_fmac_f32_dpp v105, v105, v111 row_shl:8 row_mask:0xf bank_mask:0xf
v_mul_f32_dpp v186, v186, v186 row_shl:8 row_mask:0xf bank_mask:0xf
v_mul_f32_dpp v123, v123, v123 row_shl:8 row_mask:0xf bank_mask:0xf
v_mul_f32_dpp v110, v110, v110 row_shl:8 row_mask:0xf bank_mask:0xf
v_mul_f32_dpp v111, v111, v111 row_shl:8 row_mask:0xf bank_mask:0xf

	s_nop 1
v_fmac_f32_dpp v98, v98, v117 row_shl:1 row_mask:0xf bank_mask:0xf
v_fmac_f32_dpp v99, v99, v127 row_shl:1 row_mask:0xf bank_mask:0xf
v_fmac_f32_dpp v96, v96, v122 row_shl:1 row_mask:0xf bank_mask:0xf
v_fmac_f32_dpp v97, v97, v125 row_shl:1 row_mask:0xf bank_mask:0xf
v_mul_f32_dpp v117, v117, v117 row_shl:1 row_mask:0xf bank_mask:0xf
v_mul_f32_dpp v127, v127, v127 row_shl:1 row_mask:0xf bank_mask:0xf
v_mul_f32_dpp v122, v122, v122 row_shl:1 row_mask:0xf bank_mask:0xf
v_mul_f32_dpp v125, v125, v125 row_shl:1 row_mask:0xf bank_mask:0xf
v_fmac_f32_dpp v98, v98, v117 row_shl:2 row_mask:0xf bank_mask:0xf
v_fmac_f32_dpp v99, v99, v127 row_shl:2 row_mask:0xf bank_mask:0xf
v_fmac_f32_dpp v96, v96, v122 row_shl:2 row_mask:0xf bank_mask:0xf
v_fmac_f32_dpp v97, v97, v125 row_shl:2 row_mask:0xf bank_mask:0xf
v_mul_f32_dpp v117, v117, v117 row_shl:2 row_mask:0xf bank_mask:0xf
v_mul_f32_dpp v127, v127, v127 row_shl:2 row_mask:0xf bank_mask:0xf
v_mul_f32_dpp v122, v122, v122 row_shl:2 row_mask:0xf bank_mask:0xf
v_mul_f32_dpp v125, v125, v125 row_shl:2 row_mask:0xf bank_mask:0xf
v_fmac_f32_dpp v98, v98, v117 row_shl:4 row_mask:0xf bank_mask:0xf
v_fmac_f32_dpp v99, v99, v127 row_shl:4 row_mask:0xf bank_mask:0xf
v_fmac_f32_dpp v96, v96, v122 row_shl:4 row_mask:0xf bank_mask:0xf
v_fmac_f32_dpp v97, v97, v125 row_shl:4 row_mask:0xf bank_mask:0xf
v_mul_f32_dpp v117, v117, v117 row_shl:4 row_mask:0xf bank_mask:0xf
v_mul_f32_dpp v127, v127, v127 row_shl:4 row_mask:0xf bank_mask:0xf
v_mul_f32_dpp v122, v122, v122 row_shl:4 row_mask:0xf bank_mask:0xf
v_mul_f32_dpp v125, v125, v125 row_shl:4 row_mask:0xf bank_mask:0xf
v_fmac_f32_dpp v98, v98, v117 row_shl:8 row_mask:0xf bank_mask:0xf
v_fmac_f32_dpp v99, v99, v127 row_shl:8 row_mask:0xf bank_mask:0xf
v_fmac_f32_dpp v96, v96, v122 row_shl:8 row_mask:0xf bank_mask:0xf
v_fmac_f32_dpp v97, v97, v125 row_shl:8 row_mask:0xf bank_mask:0xf
v_mul_f32_dpp v117, v117, v117 row_shl:8 row_mask:0xf bank_mask:0xf
v_mul_f32_dpp v127, v127, v127 row_shl:8 row_mask:0xf bank_mask:0xf
v_mul_f32_dpp v122, v122, v122 row_shl:8 row_mask:0xf bank_mask:0xf
v_mul_f32_dpp v125, v125, v125 row_shl:8 row_mask:0xf bank_mask:0xf

	v_cmp_eq_u32_e64 s[12:13], 0, v215
	s_nop 1
v_fmac_f32_dpp v120, v120, v102 row_shl:1 row_mask:0xf bank_mask:0xf
v_fmac_f32_dpp v121, v121, v103 row_shl:1 row_mask:0xf bank_mask:0xf
v_fmac_f32_dpp v108, v108, v100 row_shl:1 row_mask:0xf bank_mask:0xf
v_fmac_f32_dpp v109, v109, v101 row_shl:1 row_mask:0xf bank_mask:0xf
v_mul_f32_dpp v102, v102, v102 row_shl:1 row_mask:0xf bank_mask:0xf
v_mul_f32_dpp v103, v103, v103 row_shl:1 row_mask:0xf bank_mask:0xf
v_mul_f32_dpp v100, v100, v100 row_shl:1 row_mask:0xf bank_mask:0xf
v_mul_f32_dpp v101, v101, v101 row_shl:1 row_mask:0xf bank_mask:0xf
v_fmac_f32_dpp v120, v120, v102 row_shl:2 row_mask:0xf bank_mask:0xf
v_fmac_f32_dpp v121, v121, v103 row_shl:2 row_mask:0xf bank_mask:0xf
v_fmac_f32_dpp v108, v108, v100 row_shl:2 row_mask:0xf bank_mask:0xf
v_fmac_f32_dpp v109, v109, v101 row_shl:2 row_mask:0xf bank_mask:0xf
v_mul_f32_dpp v102, v102, v102 row_shl:2 row_mask:0xf bank_mask:0xf
v_mul_f32_dpp v103, v103, v103 row_shl:2 row_mask:0xf bank_mask:0xf
v_mul_f32_dpp v100, v100, v100 row_shl:2 row_mask:0xf bank_mask:0xf
v_mul_f32_dpp v101, v101, v101 row_shl:2 row_mask:0xf bank_mask:0xf
v_fmac_f32_dpp v120, v120, v102 row_shl:4 row_mask:0xf bank_mask:0xf
v_fmac_f32_dpp v121, v121, v103 row_shl:4 row_mask:0xf bank_mask:0xf
v_fmac_f32_dpp v108, v108, v100 row_shl:4 row_mask:0xf bank_mask:0xf
v_fmac_f32_dpp v109, v109, v101 row_shl:4 row_mask:0xf bank_mask:0xf
v_mul_f32_dpp v102, v102, v102 row_shl:4 row_mask:0xf bank_mask:0xf
v_mul_f32_dpp v103, v103, v103 row_shl:4 row_mask:0xf bank_mask:0xf
v_mul_f32_dpp v100, v100, v100 row_shl:4 row_mask:0xf bank_mask:0xf
v_mul_f32_dpp v101, v101, v101 row_shl:4 row_mask:0xf bank_mask:0xf
v_fmac_f32_dpp v120, v120, v102 row_shl:8 row_mask:0xf bank_mask:0xf
v_fmac_f32_dpp v121, v121, v103 row_shl:8 row_mask:0xf bank_mask:0xf
v_fmac_f32_dpp v108, v108, v100 row_shl:8 row_mask:0xf bank_mask:0xf
v_fmac_f32_dpp v109, v109, v101 row_shl:8 row_mask:0xf bank_mask:0xf
v_mul_f32_dpp v102, v102, v102 row_shl:8 row_mask:0xf bank_mask:0xf
v_mul_f32_dpp v103, v103, v103 row_shl:8 row_mask:0xf bank_mask:0xf
v_mul_f32_dpp v100, v100, v100 row_shl:8 row_mask:0xf bank_mask:0xf
v_mul_f32_dpp v101, v101, v101 row_shl:8 row_mask:0xf bank_mask:0xf

	ds_bpermute_b32 v77, v144, v102
	v_fmac_f32_e32 v120, 0, v102
	v_fmac_f32_e32 v121, 0, v103
	v_fmac_f32_e32 v108, 0, v100
	v_fmac_f32_e32 v109, 0, v101
	ds_bpermute_b32 v76, v144, v120
	ds_bpermute_b32 v78, v144, v121
	ds_bpermute_b32 v79, v144, v103
	ds_bpermute_b32 v80, v144, v108
	ds_bpermute_b32 v81, v144, v100
	ds_bpermute_b32 v82, v144, v109
	ds_bpermute_b32 v83, v144, v101
	s_waitcnt lgkmcnt(0)
	v_fmac_f32_e32 v98, v117, v76
	v_mul_f32_e32 v117, v117, v77
	v_fmac_f32_e32 v99, v127, v78
	v_mul_f32_e32 v118, v127, v79
	v_fmac_f32_e32 v96, v122, v80
	v_mul_f32_e32 v122, v122, v81
	v_fmac_f32_e32 v97, v125, v82
	v_mul_f32_e32 v124, v125, v83
	ds_bpermute_b32 v76, v144, v98
	ds_bpermute_b32 v77, v144, v117
	ds_bpermute_b32 v78, v144, v99
	ds_bpermute_b32 v79, v144, v118
	ds_bpermute_b32 v80, v144, v96
	ds_bpermute_b32 v81, v144, v122
	ds_bpermute_b32 v82, v144, v97
	ds_bpermute_b32 v83, v144, v124
	s_waitcnt lgkmcnt(0)
	v_fmac_f32_e32 v106, v186, v76
	v_mul_f32_e32 v125, v186, v77
	v_fmac_f32_e32 v107, v123, v78
	v_mul_f32_e32 v123, v123, v79
	v_fmac_f32_e32 v104, v110, v80
	v_mul_f32_e32 v126, v110, v81
	v_fmac_f32_e32 v105, v111, v82
	v_mul_f32_e32 v127, v111, v83
	ds_bpermute_b32 v76, v144, v106
	ds_bpermute_b32 v77, v144, v125
	ds_bpermute_b32 v78, v144, v107
	ds_bpermute_b32 v79, v144, v123
	ds_bpermute_b32 v80, v144, v104
	ds_bpermute_b32 v81, v144, v126
	ds_bpermute_b32 v82, v144, v105
	ds_bpermute_b32 v83, v144, v127
	s_waitcnt lgkmcnt(0)
	v_fmac_f32_e32 v114, v116, v76
	v_mul_f32_e32 v140, v116, v77
	v_fmac_f32_e32 v115, v189, v78
	v_mul_f32_e32 v141, v189, v79
	v_fmac_f32_e32 v112, v188, v80
	v_mul_f32_e32 v142, v188, v81
	v_fmac_f32_e32 v113, v119, v82
	v_mul_f32_e32 v119, v119, v83
	v_mov_b32_e32 v77, v114
	v_mov_b32_e32 v76, v140
	v_mov_b32_e32 v79, v115
	v_mov_b32_e32 v78, v141
	v_mov_b32_e32 v81, v112
	v_mov_b32_e32 v80, v142
	v_mov_b32_e32 v83, v113
	v_mov_b32_e32 v82, v119
	s_and_saveexec_b64 s[8:9], s[12:13]
	s_cbranch_execz .LBB0_439
	s_or_b32 s4, s47, 1
	s_mul_hi_i32 s5, s4, 0x84
	s_mulk_i32 s4, 0x84
	s_add_u32 s4, s4, s14
	s_addc_u32 s5, s5, 0
	s_mulk_i32 s5, 0x2800
	s_mul_hi_u32 s14, s4, 0x2800
	s_add_i32 s14, s14, s5
	s_mulk_i32 s4, 0x2800
	s_add_u32 s4, s77, s4
	s_addc_u32 s5, s78, s14
	v_lshl_add_u64 v[110:111], v[176:177], 3, s[4:5]
	s_waitcnt lgkmcnt(0)
	flat_store_dwordx4 v[110:111], v[76:79]
	flat_store_dwordx4 v[110:111], v[80:83] offset:16

.LBB0_441:
	v_pk_fma_f32 v[62:63], v[62:63], s[36:37], v[94:95] op_sel_hi:[1,0,1] neg_lo:[1,0,0] neg_hi:[1,0,0]
	v_pk_fma_f32 v[60:61], v[60:61], s[36:37], v[92:93] op_sel_hi:[1,0,1] neg_lo:[1,0,0] neg_hi:[1,0,0]
	v_exp_f32_e32 v62, v62
	v_exp_f32_e32 v63, v63
	v_exp_f32_e32 v60, v60
	v_exp_f32_e32 v61, v61
	v_pk_fma_f32 v[58:59], v[58:59], s[36:37], v[86:87] op_sel_hi:[1,0,1] neg_lo:[1,0,0] neg_hi:[1,0,0]
	v_pk_fma_f32 v[54:55], v[54:55], s[36:37], v[94:95] op_sel_hi:[1,0,1] neg_lo:[1,0,0] neg_hi:[1,0,0]
	v_exp_f32_e32 v58, v58
	v_exp_f32_e32 v59, v59
	v_pk_add_f32 v[62:63], v[62:63], 1.0 op_sel_hi:[1,0]
	v_exp_f32_e32 v54, v54
	v_exp_f32_e32 v55, v55
	v_pk_fma_f32 v[52:53], v[52:53], s[36:37], v[92:93] op_sel_hi:[1,0,1] neg_lo:[1,0,0] neg_hi:[1,0,0]
	v_rcp_f32_e32 v62, v62
	v_rcp_f32_e32 v63, v63
	v_pk_add_f32 v[60:61], v[60:61], 1.0 op_sel_hi:[1,0]
	v_exp_f32_e32 v52, v52
	v_exp_f32_e32 v53, v53
	v_pk_fma_f32 v[46:47], v[46:47], s[36:37], v[94:95] op_sel_hi:[1,0,1] neg_lo:[1,0,0] neg_hi:[1,0,0]
	v_rcp_f32_e32 v60, v60
	v_rcp_f32_e32 v61, v61
	v_exp_f32_e32 v46, v46
	v_exp_f32_e32 v47, v47
	v_pk_add_f32 v[58:59], v[58:59], 1.0 op_sel_hi:[1,0]
	v_pk_add_f32 v[54:55], v[54:55], 1.0 op_sel_hi:[1,0]
	v_pk_fma_f32 v[44:45], v[44:45], s[36:37], v[92:93] op_sel_hi:[1,0,1] neg_lo:[1,0,0] neg_hi:[1,0,0]
	v_rcp_f32_e32 v82, v58
	v_rcp_f32_e32 v83, v59
	v_pk_mul_f32 v[58:59], v[90:91], v[62:63]
	v_pk_fma_f32 v[56:57], v[56:57], s[36:37], v[84:85] op_sel_hi:[1,0,1] neg_lo:[1,0,0] neg_hi:[1,0,0]
	v_rcp_f32_e32 v54, v54
	v_rcp_f32_e32 v55, v55
	v_pk_add_f32 v[52:53], v[52:53], 1.0 op_sel_hi:[1,0]
	v_exp_f32_e32 v44, v44
	v_exp_f32_e32 v45, v45
	v_exp_f32_e32 v58, v58
	v_exp_f32_e32 v59, v59
	v_exp_f32_e32 v96, v56
	v_exp_f32_e32 v97, v57
	v_pk_mul_f32 v[56:57], v[88:89], v[60:61]
	v_rcp_f32_e32 v52, v52
	v_rcp_f32_e32 v53, v53
	v_pk_add_f32 v[46:47], v[46:47], 1.0 op_sel_hi:[1,0]
	v_pk_fma_f32 v[38:39], v[38:39], s[36:37], v[94:95] op_sel_hi:[1,0,1] neg_lo:[1,0,0] neg_hi:[1,0,0]
	v_pk_fma_f32 v[36:37], v[36:37], s[36:37], v[92:93] op_sel_hi:[1,0,1] neg_lo:[1,0,0] neg_hi:[1,0,0]
	v_exp_f32_e32 v56, v56
	v_exp_f32_e32 v57, v57
	v_rcp_f32_e32 v46, v46
	v_rcp_f32_e32 v47, v47
	v_exp_f32_e32 v38, v38
	v_exp_f32_e32 v39, v39
	v_exp_f32_e32 v36, v36
	v_exp_f32_e32 v37, v37
	v_pk_fma_f32 v[50:51], v[50:51], s[36:37], v[86:87] op_sel_hi:[1,0,1] neg_lo:[1,0,0] neg_hi:[1,0,0]
	v_pk_mul_f32 v[54:55], v[90:91], v[54:55]
	v_exp_f32_e32 v50, v50
	v_exp_f32_e32 v51, v51
	v_pk_fma_f32 v[48:49], v[48:49], s[36:37], v[84:85] op_sel_hi:[1,0,1] neg_lo:[1,0,0] neg_hi:[1,0,0]
	v_pk_add_f32 v[44:45], v[44:45], 1.0 op_sel_hi:[1,0]
	v_pk_fma_f32 v[62:63], v[58:59], v[58:59], 1.0 op_sel_hi:[1,1,0] neg_lo:[1,0,0] neg_hi:[1,0,0]
	v_pk_add_f32 v[60:61], v[96:97], 1.0 op_sel_hi:[1,0]
	v_exp_f32_e32 v102, v54
	v_exp_f32_e32 v103, v55
	v_exp_f32_e32 v48, v48
	v_exp_f32_e32 v49, v49
	v_pk_mul_f32 v[52:53], v[88:89], v[52:53]
	v_pk_fma_f32 v[42:43], v[42:43], s[36:37], v[86:87] op_sel_hi:[1,0,1] neg_lo:[1,0,0] neg_hi:[1,0,0]
	v_rcp_f32_e32 v44, v44
	v_rcp_f32_e32 v45, v45
	v_sqrt_f32_e32 v62, v62
	v_sqrt_f32_e32 v63, v63
	v_rcp_f32_e32 v96, v60
	v_rcp_f32_e32 v97, v61
	v_pk_fma_f32 v[60:61], v[56:57], v[56:57], 1.0 op_sel_hi:[1,1,0] neg_lo:[1,0,0] neg_hi:[1,0,0]
	v_exp_f32_e32 v104, v52
	v_exp_f32_e32 v105, v53
	v_exp_f32_e32 v42, v42
	v_exp_f32_e32 v43, v43
	v_pk_mul_f32 v[46:47], v[90:91], v[46:47]
	v_pk_fma_f32 v[40:41], v[40:41], s[36:37], v[84:85] op_sel_hi:[1,0,1] neg_lo:[1,0,0] neg_hi:[1,0,0]
	v_pk_add_f32 v[38:39], v[38:39], 1.0 op_sel_hi:[1,0]
	v_pk_add_f32 v[36:37], v[36:37], 1.0 op_sel_hi:[1,0]
	v_sqrt_f32_e32 v98, v60
	v_sqrt_f32_e32 v99, v61
	v_exp_f32_e32 v106, v46
	v_exp_f32_e32 v107, v47
	v_exp_f32_e32 v40, v40
	v_exp_f32_e32 v41, v41
	v_rcp_f32_e32 v38, v38
	v_rcp_f32_e32 v39, v39
	v_rcp_f32_e32 v36, v36
	v_rcp_f32_e32 v37, v37
	v_lshlrev_b32_e32 v80, 16, v171
	v_and_b32_e32 v81, 0xffff0000, v171
	v_pk_add_f32 v[50:51], v[50:51], 1.0 op_sel_hi:[1,0]
	v_lshlrev_b32_e32 v78, 16, v170
	v_and_b32_e32 v79, 0xffff0000, v170
	v_pk_mul_f32 v[60:61], v[82:83], v[80:81]
	v_rcp_f32_e32 v50, v50
	v_rcp_f32_e32 v51, v51
	v_pk_fma_f32 v[54:55], v[102:103], v[102:103], 1.0 op_sel_hi:[1,1,0] neg_lo:[1,0,0] neg_hi:[1,0,0]
	v_pk_add_f32 v[48:49], v[48:49], 1.0 op_sel_hi:[1,0]
	v_pk_mul_f32 v[44:45], v[88:89], v[44:45]
	v_pk_mul_f32 v[60:61], v[60:61], v[62:63]
	v_pk_mul_f32 v[62:63], v[96:97], v[78:79]
	v_sqrt_f32_e32 v54, v54
	v_sqrt_f32_e32 v55, v55
	v_rcp_f32_e32 v52, v48
	v_rcp_f32_e32 v53, v49
	v_pk_fma_f32 v[48:49], v[104:105], v[104:105], 1.0 op_sel_hi:[1,1,0] neg_lo:[1,0,0] neg_hi:[1,0,0]
	v_pk_add_f32 v[42:43], v[42:43], 1.0 op_sel_hi:[1,0]
	v_exp_f32_e32 v108, v44
	v_exp_f32_e32 v109, v45
	v_pk_fma_f32 v[34:35], v[34:35], s[36:37], v[86:87] op_sel_hi:[1,0,1] neg_lo:[1,0,0] neg_hi:[1,0,0]
	v_pk_fma_f32 v[32:33], v[32:33], s[36:37], v[84:85] op_sel_hi:[1,0,1] neg_lo:[1,0,0] neg_hi:[1,0,0]
	v_pk_mul_f32 v[62:63], v[62:63], v[98:99]
	v_sqrt_f32_e32 v98, v48
	v_sqrt_f32_e32 v99, v49
	v_rcp_f32_e32 v42, v42
	v_rcp_f32_e32 v43, v43
	v_pk_fma_f32 v[46:47], v[106:107], v[106:107], 1.0 op_sel_hi:[1,1,0] neg_lo:[1,0,0] neg_hi:[1,0,0]
	v_pk_add_f32 v[40:41], v[40:41], 1.0 op_sel_hi:[1,0]
	v_exp_f32_e32 v34, v34
	v_exp_f32_e32 v35, v35
	v_pk_mul_f32 v[38:39], v[90:91], v[38:39]
	v_exp_f32_e32 v32, v32
	v_exp_f32_e32 v33, v33
	v_pk_mul_f32 v[36:37], v[88:89], v[36:37]
	v_lshlrev_b32_e32 v96, 16, v169
	v_and_b32_e32 v97, 0xffff0000, v169
	v_sqrt_f32_e32 v46, v46
	v_sqrt_f32_e32 v47, v47
	v_rcp_f32_e32 v44, v40
	v_rcp_f32_e32 v45, v41
	v_exp_f32_e32 v38, v38
	v_exp_f32_e32 v39, v39
	v_exp_f32_e32 v36, v36
	v_exp_f32_e32 v37, v37
	v_lshlrev_b32_e32 v82, 16, v168
	v_and_b32_e32 v83, 0xffff0000, v168
	v_pk_mul_f32 v[48:49], v[50:51], v[96:97]
	v_pk_mul_f32 v[50:51], v[52:53], v[82:83]
	v_pk_mul_f32 v[48:49], v[48:49], v[54:55]
	v_lshlrev_b32_e32 v54, 16, v167
	v_and_b32_e32 v55, 0xffff0000, v167
	v_pk_fma_f32 v[40:41], v[108:109], v[108:109], 1.0 op_sel_hi:[1,1,0] neg_lo:[1,0,0] neg_hi:[1,0,0]
	v_pk_mul_f32 v[50:51], v[50:51], v[98:99]
	v_lshlrev_b32_e32 v52, 16, v166
	v_and_b32_e32 v53, 0xffff0000, v166
	v_sqrt_f32_e32 v98, v40
	v_sqrt_f32_e32 v99, v41
	v_pk_mul_f32 v[40:41], v[42:43], v[54:55]
	v_pk_add_f32 v[34:35], v[34:35], 1.0 op_sel_hi:[1,0]
	v_pk_add_f32 v[32:33], v[32:33], 1.0 op_sel_hi:[1,0]
	v_pk_mul_f32 v[40:41], v[40:41], v[46:47]
	v_pk_mul_f32 v[42:43], v[44:45], v[52:53]
	v_rcp_f32_e32 v34, v34
	v_rcp_f32_e32 v35, v35
	v_pk_fma_f32 v[44:45], v[38:39], v[38:39], 1.0 op_sel_hi:[1,1,0] neg_lo:[1,0,0] neg_hi:[1,0,0]
	v_rcp_f32_e32 v32, v32
	v_rcp_f32_e32 v33, v33
	v_pk_fma_f32 v[46:47], v[36:37], v[36:37], 1.0 op_sel_hi:[1,1,0] neg_lo:[1,0,0] neg_hi:[1,0,0]
	v_sqrt_f32_e32 v44, v44
	v_sqrt_f32_e32 v45, v45
	v_sqrt_f32_e32 v46, v46
	v_sqrt_f32_e32 v47, v47
	s_nop 1
v_fmac_f32_dpp v62, v62, v56 row_shr:1 row_mask:0xf bank_mask:0xf
v_fmac_f32_dpp v63, v63, v57 row_shr:1 row_mask:0xf bank_mask:0xf
v_fmac_f32_dpp v60, v60, v58 row_shr:1 row_mask:0xf bank_mask:0xf
v_fmac_f32_dpp v61, v61, v59 row_shr:1 row_mask:0xf bank_mask:0xf
v_mul_f32_dpp v56, v56, v56 row_shr:1 row_mask:0xf bank_mask:0xf
v_mul_f32_dpp v57, v57, v57 row_shr:1 row_mask:0xf bank_mask:0xf
v_mul_f32_dpp v58, v58, v58 row_shr:1 row_mask:0xf bank_mask:0xf
v_mul_f32_dpp v59, v59, v59 row_shr:1 row_mask:0xf bank_mask:0xf
v_fmac_f32_dpp v62, v62, v56 row_shr:2 row_mask:0xf bank_mask:0xf
v_fmac_f32_dpp v63, v63, v57 row_shr:2 row_mask:0xf bank_mask:0xf
v_fmac_f32_dpp v60, v60, v58 row_shr:2 row_mask:0xf bank_mask:0xf
v_fmac_f32_dpp v61, v61, v59 row_shr:2 row_mask:0xf bank_mask:0xf
v_mul_f32_dpp v56, v56, v56 row_shr:2 row_mask:0xf bank_mask:0xf
v_mul_f32_dpp v57, v57, v57 row_shr:2 row_mask:0xf bank_mask:0xf
v_mul_f32_dpp v58, v58, v58 row_shr:2 row_mask:0xf bank_mask:0xf
v_mul_f32_dpp v59, v59, v59 row_shr:2 row_mask:0xf bank_mask:0xf
v_fmac_f32_dpp v62, v62, v56 row_shr:4 row_mask:0xf bank_mask:0xf
v_fmac_f32_dpp v63, v63, v57 row_shr:4 row_mask:0xf bank_mask:0xf
v_fmac_f32_dpp v60, v60, v58 row_shr:4 row_mask:0xf bank_mask:0xf
v_fmac_f32_dpp v61, v61, v59 row_shr:4 row_mask:0xf bank_mask:0xf
v_mul_f32_dpp v56, v56, v56 row_shr:4 row_mask:0xf bank_mask:0xf
v_mul_f32_dpp v57, v57, v57 row_shr:4 row_mask:0xf bank_mask:0xf
v_mul_f32_dpp v58, v58, v58 row_shr:4 row_mask:0xf bank_mask:0xf
v_mul_f32_dpp v59, v59, v59 row_shr:4 row_mask:0xf bank_mask:0xf
v_fmac_f32_dpp v62, v62, v56 row_shr:8 row_mask:0xf bank_mask:0xf
v_fmac_f32_dpp v63, v63, v57 row_shr:8 row_mask:0xf bank_mask:0xf
v_fmac_f32_dpp v60, v60, v58 row_shr:8 row_mask:0xf bank_mask:0xf
v_fmac_f32_dpp v61, v61, v59 row_shr:8 row_mask:0xf bank_mask:0xf
v_mul_f32_dpp v56, v56, v56 row_shr:8 row_mask:0xf bank_mask:0xf
v_mul_f32_dpp v57, v57, v57 row_shr:8 row_mask:0xf bank_mask:0xf
v_mul_f32_dpp v58, v58, v58 row_shr:8 row_mask:0xf bank_mask:0xf
v_mul_f32_dpp v59, v59, v59 row_shr:8 row_mask:0xf bank_mask:0xf

	v_pk_mul_f32 v[42:43], v[42:43], v[98:99]
	v_lshlrev_b32_e32 v98, 16, v164
	v_and_b32_e32 v99, 0xffff0000, v164
	v_lshlrev_b32_e32 v100, 16, v165
	v_and_b32_e32 v101, 0xffff0000, v165
	v_or_b32_e32 v112, 60, v144
	v_pk_mul_f32 v[34:35], v[34:35], v[100:101]
	v_pk_mul_f32 v[32:33], v[32:33], v[98:99]
	v_fmac_f32_e32 v62, 0, v56
	v_fmac_f32_e32 v63, 0, v57
	v_fmac_f32_e32 v60, 0, v58
	v_fmac_f32_e32 v61, 0, v59
	v_pk_mul_f32 v[44:45], v[34:35], v[44:45]
	v_pk_mul_f32 v[46:47], v[32:33], v[46:47]
	v_mov_b32_e32 v32, v36
	v_mov_b32_e32 v36, v38
	ds_bpermute_b32 v33, v112, v62
	ds_bpermute_b32 v34, v112, v56
	ds_bpermute_b32 v35, v112, v63
	ds_bpermute_b32 v38, v112, v57
	ds_bpermute_b32 v84, v112, v60
	ds_bpermute_b32 v85, v112, v58
	ds_bpermute_b32 v86, v112, v61
	ds_bpermute_b32 v87, v112, v59
	s_nop 1
v_fmac_f32_dpp v50, v50, v104 row_shr:1 row_mask:0xf bank_mask:0xf
v_fmac_f32_dpp v51, v51, v105 row_shr:1 row_mask:0xf bank_mask:0xf
v_fmac_f32_dpp v48, v48, v102 row_shr:1 row_mask:0xf bank_mask:0xf
v_fmac_f32_dpp v49, v49, v103 row_shr:1 row_mask:0xf bank_mask:0xf
v_mul_f32_dpp v104, v104, v104 row_shr:1 row_mask:0xf bank_mask:0xf
v_mul_f32_dpp v105, v105, v105 row_shr:1 row_mask:0xf bank_mask:0xf
v_mul_f32_dpp v102, v102, v102 row_shr:1 row_mask:0xf bank_mask:0xf
v_mul_f32_dpp v103, v103, v103 row_shr:1 row_mask:0xf bank_mask:0xf
v_fmac_f32_dpp v50, v50, v104 row_shr:2 row_mask:0xf bank_mask:0xf
v_fmac_f32_dpp v51, v51, v105 row_shr:2 row_mask:0xf bank_mask:0xf
v_fmac_f32_dpp v48, v48, v102 row_shr:2 row_mask:0xf bank_mask:0xf
v_fmac_f32_dpp v49, v49, v103 row_shr:2 row_mask:0xf bank_mask:0xf
v_mul_f32_dpp v104, v104, v104 row_shr:2 row_mask:0xf bank_mask:0xf
v_mul_f32_dpp v105, v105, v105 row_shr:2 row_mask:0xf bank_mask:0xf
v_mul_f32_dpp v102, v102, v102 row_shr:2 row_mask:0xf bank_mask:0xf
v_mul_f32_dpp v103, v103, v103 row_shr:2 row_mask:0xf bank_mask:0xf
v_fmac_f32_dpp v50, v50, v104 row_shr:4 row_mask:0xf bank_mask:0xf
v_fmac_f32_dpp v51, v51, v105 row_shr:4 row_mask:0xf bank_mask:0xf
v_fmac_f32_dpp v48, v48, v102 row_shr:4 row_mask:0xf bank_mask:0xf
v_fmac_f32_dpp v49, v49, v103 row_shr:4 row_mask:0xf bank_mask:0xf
v_mul_f32_dpp v104, v104, v104 row_shr:4 row_mask:0xf bank_mask:0xf
v_mul_f32_dpp v105, v105, v105 row_shr:4 row_mask:0xf bank_mask:0xf
v_mul_f32_dpp v102, v102, v102 row_shr:4 row_mask:0xf bank_mask:0xf
v_mul_f32_dpp v103, v103, v103 row_shr:4 row_mask:0xf bank_mask:0xf
v_fmac_f32_dpp v50, v50, v104 row_shr:8 row_mask:0xf bank_mask:0xf
v_fmac_f32_dpp v51, v51, v105 row_shr:8 row_mask:0xf bank_mask:0xf
v_fmac_f32_dpp v48, v48, v102 row_shr:8 row_mask:0xf bank_mask:0xf
v_fmac_f32_dpp v49, v49, v103 row_shr:8 row_mask:0xf bank_mask:0xf
v_mul_f32_dpp v104, v104, v104 row_shr:8 row_mask:0xf bank_mask:0xf
v_mul_f32_dpp v105, v105, v105 row_shr:8 row_mask:0xf bank_mask:0xf
v_mul_f32_dpp v102, v102, v102 row_shr:8 row_mask:0xf bank_mask:0xf
v_mul_f32_dpp v103, v103, v103 row_shr:8 row_mask:0xf bank_mask:0xf

	s_nop 1
v_fmac_f32_dpp v42, v42, v108 row_shr:1 row_mask:0xf bank_mask:0xf
v_fmac_f32_dpp v43, v43, v109 row_shr:1 row_mask:0xf bank_mask:0xf
v_fmac_f32_dpp v40, v40, v106 row_shr:1 row_mask:0xf bank_mask:0xf
v_fmac_f32_dpp v41, v41, v107 row_shr:1 row_mask:0xf bank_mask:0xf
v_mul_f32_dpp v108, v108, v108 row_shr:1 row_mask:0xf bank_mask:0xf
v_mul_f32_dpp v109, v109, v109 row_shr:1 row_mask:0xf bank_mask:0xf
v_mul_f32_dpp v106, v106, v106 row_shr:1 row_mask:0xf bank_mask:0xf
v_mul_f32_dpp v107, v107, v107 row_shr:1 row_mask:0xf bank_mask:0xf
v_fmac_f32_dpp v42, v42, v108 row_shr:2 row_mask:0xf bank_mask:0xf
v_fmac_f32_dpp v43, v43, v109 row_shr:2 row_mask:0xf bank_mask:0xf
v_fmac_f32_dpp v40, v40, v106 row_shr:2 row_mask:0xf bank_mask:0xf
v_fmac_f32_dpp v41, v41, v107 row_shr:2 row_mask:0xf bank_mask:0xf
v_mul_f32_dpp v108, v108, v108 row_shr:2 row_mask:0xf bank_mask:0xf
v_mul_f32_dpp v109, v109, v109 row_shr:2 row_mask:0xf bank_mask:0xf
v_mul_f32_dpp v106, v106, v106 row_shr:2 row_mask:0xf bank_mask:0xf
v_mul_f32_dpp v107, v107, v107 row_shr:2 row_mask:0xf bank_mask:0xf
v_fmac_f32_dpp v42, v42, v108 row_shr:4 row_mask:0xf bank_mask:0xf
v_fmac_f32_dpp v43, v43, v109 row_shr:4 row_mask:0xf bank_mask:0xf
v_fmac_f32_dpp v40, v40, v106 row_shr:4 row_mask:0xf bank_mask:0xf
v_fmac_f32_dpp v41, v41, v107 row_shr:4 row_mask:0xf bank_mask:0xf
v_mul_f32_dpp v108, v108, v108 row_shr:4 row_mask:0xf bank_mask:0xf
v_mul_f32_dpp v109, v109, v109 row_shr:4 row_mask:0xf bank_mask:0xf
v_mul_f32_dpp v106, v106, v106 row_shr:4 row_mask:0xf bank_mask:0xf
v_mul_f32_dpp v107, v107, v107 row_shr:4 row_mask:0xf bank_mask:0xf
v_fmac_f32_dpp v42, v42, v108 row_shr:8 row_mask:0xf bank_mask:0xf
v_fmac_f32_dpp v43, v43, v109 row_shr:8 row_mask:0xf bank_mask:0xf
v_fmac_f32_dpp v40, v40, v106 row_shr:8 row_mask:0xf bank_mask:0xf
v_fmac_f32_dpp v41, v41, v107 row_shr:8 row_mask:0xf bank_mask:0xf
v_mul_f32_dpp v108, v108, v108 row_shr:8 row_mask:0xf bank_mask:0xf
v_mul_f32_dpp v109, v109, v109 row_shr:8 row_mask:0xf bank_mask:0xf
v_mul_f32_dpp v106, v106, v106 row_shr:8 row_mask:0xf bank_mask:0xf
v_mul_f32_dpp v107, v107, v107 row_shr:8 row_mask:0xf bank_mask:0xf

	s_nop 1
v_fmac_f32_dpp v46, v46, v32 row_shr:1 row_mask:0xf bank_mask:0xf
v_fmac_f32_dpp v47, v47, v37 row_shr:1 row_mask:0xf bank_mask:0xf
v_fmac_f32_dpp v44, v44, v36 row_shr:1 row_mask:0xf bank_mask:0xf
v_fmac_f32_dpp v45, v45, v39 row_shr:1 row_mask:0xf bank_mask:0xf
v_mul_f32_dpp v32, v32, v32 row_shr:1 row_mask:0xf bank_mask:0xf
v_mul_f32_dpp v37, v37, v37 row_shr:1 row_mask:0xf bank_mask:0xf
v_mul_f32_dpp v36, v36, v36 row_shr:1 row_mask:0xf bank_mask:0xf
v_mul_f32_dpp v39, v39, v39 row_shr:1 row_mask:0xf bank_mask:0xf
v_fmac_f32_dpp v46, v46, v32 row_shr:2 row_mask:0xf bank_mask:0xf
v_fmac_f32_dpp v47, v47, v37 row_shr:2 row_mask:0xf bank_mask:0xf
v_fmac_f32_dpp v44, v44, v36 row_shr:2 row_mask:0xf bank_mask:0xf
v_fmac_f32_dpp v45, v45, v39 row_shr:2 row_mask:0xf bank_mask:0xf
v_mul_f32_dpp v32, v32, v32 row_shr:2 row_mask:0xf bank_mask:0xf
v_mul_f32_dpp v37, v37, v37 row_shr:2 row_mask:0xf bank_mask:0xf
v_mul_f32_dpp v36, v36, v36 row_shr:2 row_mask:0xf bank_mask:0xf
v_mul_f32_dpp v39, v39, v39 row_shr:2 row_mask:0xf bank_mask:0xf
v_fmac_f32_dpp v46, v46, v32 row_shr:4 row_mask:0xf bank_mask:0xf
v_fmac_f32_dpp v47, v47, v37 row_shr:4 row_mask:0xf bank_mask:0xf
v_fmac_f32_dpp v44, v44, v36 row_shr:4 row_mask:0xf bank_mask:0xf
v_fmac_f32_dpp v45, v45, v39 row_shr:4 row_mask:0xf bank_mask:0xf
v_mul_f32_dpp v32, v32, v32 row_shr:4 row_mask:0xf bank_mask:0xf
v_mul_f32_dpp v37, v37, v37 row_shr:4 row_mask:0xf bank_mask:0xf
v_mul_f32_dpp v36, v36, v36 row_shr:4 row_mask:0xf bank_mask:0xf
v_mul_f32_dpp v39, v39, v39 row_shr:4 row_mask:0xf bank_mask:0xf
v_fmac_f32_dpp v46, v46, v32 row_shr:8 row_mask:0xf bank_mask:0xf
v_fmac_f32_dpp v47, v47, v37 row_shr:8 row_mask:0xf bank_mask:0xf
v_fmac_f32_dpp v44, v44, v36 row_shr:8 row_mask:0xf bank_mask:0xf
v_fmac_f32_dpp v45, v45, v39 row_shr:8 row_mask:0xf bank_mask:0xf
v_mul_f32_dpp v32, v32, v32 row_shr:8 row_mask:0xf bank_mask:0xf
v_mul_f32_dpp v37, v37, v37 row_shr:8 row_mask:0xf bank_mask:0xf
v_mul_f32_dpp v36, v36, v36 row_shr:8 row_mask:0xf bank_mask:0xf
v_mul_f32_dpp v39, v39, v39 row_shr:8 row_mask:0xf bank_mask:0xf

	s_add_i32 s49, s49, 6
	s_waitcnt lgkmcnt(0)
	v_fmac_f32_e32 v50, v104, v33
	v_mul_f32_e32 v92, v104, v34
	v_fmac_f32_e32 v51, v105, v35
	v_mul_f32_e32 v93, v105, v38
	v_fmac_f32_e32 v48, v102, v84
	v_mul_f32_e32 v94, v102, v85
	v_fmac_f32_e32 v49, v103, v86
	v_mul_f32_e32 v95, v103, v87
	ds_bpermute_b32 v33, v112, v50
	ds_bpermute_b32 v34, v112, v92
	ds_bpermute_b32 v35, v112, v51
	ds_bpermute_b32 v38, v112, v93
	ds_bpermute_b32 v84, v112, v48
	ds_bpermute_b32 v85, v112, v94
	ds_bpermute_b32 v87, v112, v49
	ds_bpermute_b32 v89, v112, v95
	s_waitcnt lgkmcnt(0)
	v_fmac_f32_e32 v42, v108, v33
	v_mul_f32_e32 v86, v108, v34
	v_fmac_f32_e32 v43, v109, v35
	v_mul_f32_e32 v88, v109, v38
	v_fmac_f32_e32 v40, v106, v84
	v_mul_f32_e32 v90, v106, v85
	v_fmac_f32_e32 v41, v107, v87
	v_mul_f32_e32 v91, v107, v89
	ds_bpermute_b32 v33, v112, v42
	ds_bpermute_b32 v34, v112, v86
	ds_bpermute_b32 v35, v112, v43
	ds_bpermute_b32 v38, v112, v88
	ds_bpermute_b32 v102, v112, v40
	ds_bpermute_b32 v103, v112, v90
	ds_bpermute_b32 v89, v112, v41
	ds_bpermute_b32 v104, v112, v91
	s_waitcnt lgkmcnt(0)
	v_fmac_f32_e32 v46, v32, v33
	v_mul_f32_e32 v84, v32, v34
	v_fmac_f32_e32 v47, v37, v35
	v_mul_f32_e32 v85, v37, v38
	v_fmac_f32_e32 v44, v36, v102
	v_mul_f32_e32 v87, v36, v103
	v_fmac_f32_e32 v45, v39, v89
	v_mul_f32_e32 v89, v39, v104
	v_mov_b32_e32 v33, v46
	v_mov_b32_e32 v32, v84
	v_mov_b32_e32 v35, v47
	v_mov_b32_e32 v34, v85
	v_mov_b32_e32 v37, v44
	v_mov_b32_e32 v36, v87
	v_mov_b32_e32 v39, v45
	v_mov_b32_e32 v38, v89
	s_and_b64 s[4:5], exec, s[54:55]
	s_cselect_b32 s49, 2, s49
	s_add_i32 s49, s49, s66
	s_and_saveexec_b64 s[54:55], s[10:11]
	s_cbranch_execz .LBB0_443
	s_add_u32 s4, s59, s49
	s_addc_u32 s5, s58, 0
	s_mulk_i32 s5, 0x2800
	s_mul_hi_u32 s10, s4, 0x2800
	s_add_i32 s10, s10, s5
	s_mulk_i32 s4, 0x2800
	s_add_u32 s4, s77, s4
	s_addc_u32 s5, s78, s10
	v_lshl_add_u64 v[102:103], v[176:177], 3, s[4:5]
	s_waitcnt lgkmcnt(0)
	flat_store_dwordx4 v[102:103], v[32:35]
	flat_store_dwordx4 v[102:103], v[36:39] offset:16
.LBB0_443:
	s_or_b64 exec, exec, s[54:55]
	v_pk_fma_f32 v[30:31], v[30:31], s[36:37], v[74:75] op_sel_hi:[1,0,1] neg_lo:[1,0,0] neg_hi:[1,0,0]
	v_pk_fma_f32 v[26:27], v[26:27], s[36:37], v[70:71] op_sel_hi:[1,0,1] neg_lo:[1,0,0] neg_hi:[1,0,0]
	v_exp_f32_e32 v30, v30
	v_exp_f32_e32 v31, v31
	v_exp_f32_e32 v26, v26
	v_exp_f32_e32 v27, v27
	v_pk_fma_f32 v[28:29], v[28:29], s[36:37], v[72:73] op_sel_hi:[1,0,1] neg_lo:[1,0,0] neg_hi:[1,0,0]
	v_pk_add_f32 v[30:31], v[30:31], 1.0 op_sel_hi:[1,0]
	v_exp_f32_e32 v28, v28
	v_rcp_f32_e32 v30, v30
	v_rcp_f32_e32 v31, v31
	v_exp_f32_e32 v29, v29
	v_pk_add_f32 v[26:27], v[26:27], 1.0 op_sel_hi:[1,0]
	v_pk_fma_f32 v[20:21], v[20:21], s[36:37], v[72:73] op_sel_hi:[1,0,1] neg_lo:[1,0,0] neg_hi:[1,0,0]
	s_waitcnt lgkmcnt(0)
	v_rcp_f32_e32 v32, v26
	v_rcp_f32_e32 v33, v27
	v_pk_mul_f32 v[26:27], v[66:67], v[30:31]
	v_pk_add_f32 v[28:29], v[28:29], 1.0 op_sel_hi:[1,0]
	v_exp_f32_e32 v26, v26
	v_exp_f32_e32 v27, v27
	v_rcp_f32_e32 v28, v28
	v_rcp_f32_e32 v29, v29
	v_exp_f32_e32 v20, v20
	v_exp_f32_e32 v21, v21
	v_pk_fma_f32 v[24:25], v[24:25], s[36:37], v[68:69] op_sel_hi:[1,0,1] neg_lo:[1,0,0] neg_hi:[1,0,0]
	v_pk_fma_f32 v[30:31], v[26:27], v[26:27], 1.0 op_sel_hi:[1,1,0] neg_lo:[1,0,0] neg_hi:[1,0,0]
	v_exp_f32_e32 v24, v24
	v_exp_f32_e32 v25, v25
	v_pk_mul_f32 v[28:29], v[64:65], v[28:29]
	v_sqrt_f32_e32 v34, v30
	v_sqrt_f32_e32 v35, v31
	v_exp_f32_e32 v30, v28
	v_exp_f32_e32 v31, v29
	v_pk_add_f32 v[20:21], v[20:21], 1.0 op_sel_hi:[1,0]
	v_pk_add_f32 v[24:25], v[24:25], 1.0 op_sel_hi:[1,0]
	v_rcp_f32_e32 v20, v20
	v_rcp_f32_e32 v21, v21
	v_rcp_f32_e32 v28, v24
	v_rcp_f32_e32 v29, v25
	v_pk_fma_f32 v[24:25], v[30:31], v[30:31], 1.0 op_sel_hi:[1,1,0] neg_lo:[1,0,0] neg_hi:[1,0,0]
	v_pk_fma_f32 v[18:19], v[18:19], s[36:37], v[70:71] op_sel_hi:[1,0,1] neg_lo:[1,0,0] neg_hi:[1,0,0]
	v_pk_fma_f32 v[16:17], v[16:17], s[36:37], v[68:69] op_sel_hi:[1,0,1] neg_lo:[1,0,0] neg_hi:[1,0,0]
	v_pk_fma_f32 v[14:15], v[14:15], s[36:37], v[74:75] op_sel_hi:[1,0,1] neg_lo:[1,0,0] neg_hi:[1,0,0]
	v_sqrt_f32_e32 v36, v24
	v_sqrt_f32_e32 v37, v25
	v_pk_mul_f32 v[24:25], v[32:33], v[80:81]
	v_exp_f32_e32 v18, v18
	v_exp_f32_e32 v19, v19
	v_exp_f32_e32 v16, v16
	v_exp_f32_e32 v17, v17
	v_pk_mul_f32 v[20:21], v[64:65], v[20:21]
	v_exp_f32_e32 v14, v14
	v_exp_f32_e32 v15, v15
	v_pk_mul_f32 v[24:25], v[24:25], v[34:35]
	v_exp_f32_e32 v34, v20
	v_exp_f32_e32 v35, v21
	v_pk_fma_f32 v[12:13], v[12:13], s[36:37], v[72:73] op_sel_hi:[1,0,1] neg_lo:[1,0,0] neg_hi:[1,0,0]
	v_pk_add_f32 v[18:19], v[18:19], 1.0 op_sel_hi:[1,0]
	v_exp_f32_e32 v12, v12
	v_exp_f32_e32 v13, v13
	v_pk_add_f32 v[16:17], v[16:17], 1.0 op_sel_hi:[1,0]
	v_pk_add_f32 v[14:15], v[14:15], 1.0 op_sel_hi:[1,0]
	v_pk_mul_f32 v[28:29], v[28:29], v[78:79]
	v_rcp_f32_e32 v18, v18
	v_rcp_f32_e32 v19, v19
	v_rcp_f32_e32 v20, v16
	v_rcp_f32_e32 v21, v17
	v_pk_fma_f32 v[16:17], v[34:35], v[34:35], 1.0 op_sel_hi:[1,1,0] neg_lo:[1,0,0] neg_hi:[1,0,0]
	v_rcp_f32_e32 v14, v14
	v_rcp_f32_e32 v15, v15
	v_pk_mul_f32 v[28:29], v[28:29], v[36:37]
	v_sqrt_f32_e32 v36, v16
	v_sqrt_f32_e32 v37, v17
	v_pk_add_f32 v[12:13], v[12:13], 1.0 op_sel_hi:[1,0]
	v_pk_fma_f32 v[22:23], v[22:23], s[36:37], v[74:75] op_sel_hi:[1,0,1] neg_lo:[1,0,0] neg_hi:[1,0,0]
	v_pk_fma_f32 v[10:11], v[10:11], s[36:37], v[70:71] op_sel_hi:[1,0,1] neg_lo:[1,0,0] neg_hi:[1,0,0]
	v_rcp_f32_e32 v12, v12
	v_rcp_f32_e32 v13, v13
	v_pk_fma_f32 v[6:7], v[6:7], s[36:37], v[74:75] op_sel_hi:[1,0,1] neg_lo:[1,0,0] neg_hi:[1,0,0]
	v_pk_fma_f32 v[4:5], v[4:5], s[36:37], v[72:73] op_sel_hi:[1,0,1] neg_lo:[1,0,0] neg_hi:[1,0,0]
	v_exp_f32_e32 v22, v22
	v_exp_f32_e32 v23, v23
	v_pk_mul_f32 v[16:17], v[18:19], v[96:97]
	v_pk_mul_f32 v[18:19], v[20:21], v[82:83]
	v_exp_f32_e32 v10, v10
	v_exp_f32_e32 v11, v11
	v_pk_mul_f32 v[14:15], v[66:67], v[14:15]
	v_pk_fma_f32 v[8:9], v[8:9], s[36:37], v[68:69] op_sel_hi:[1,0,1] neg_lo:[1,0,0] neg_hi:[1,0,0]
	v_exp_f32_e32 v6, v6
	v_exp_f32_e32 v7, v7
	v_exp_f32_e32 v4, v4
	v_exp_f32_e32 v5, v5
	v_pk_mul_f32 v[18:19], v[18:19], v[36:37]
	v_exp_f32_e32 v36, v14
	v_exp_f32_e32 v37, v15
	v_exp_f32_e32 v8, v8
	v_exp_f32_e32 v9, v9
	v_pk_mul_f32 v[12:13], v[64:65], v[12:13]
	v_pk_add_f32 v[22:23], v[22:23], 1.0 op_sel_hi:[1,0]
	v_pk_add_f32 v[10:11], v[10:11], 1.0 op_sel_hi:[1,0]
	v_exp_f32_e32 v38, v12
	v_exp_f32_e32 v39, v13
	v_pk_add_f32 v[6:7], v[6:7], 1.0 op_sel_hi:[1,0]
	v_pk_add_f32 v[4:5], v[4:5], 1.0 op_sel_hi:[1,0]
	v_rcp_f32_e32 v22, v22
	v_rcp_f32_e32 v23, v23
	v_rcp_f32_e32 v10, v10
	v_rcp_f32_e32 v11, v11
	v_pk_fma_f32 v[14:15], v[36:37], v[36:37], 1.0 op_sel_hi:[1,1,0] neg_lo:[1,0,0] neg_hi:[1,0,0]
	v_pk_add_f32 v[8:9], v[8:9], 1.0 op_sel_hi:[1,0]
	v_rcp_f32_e32 v6, v6
	v_rcp_f32_e32 v7, v7
	v_rcp_f32_e32 v4, v4
	v_rcp_f32_e32 v5, v5
	v_sqrt_f32_e32 v14, v14
	v_sqrt_f32_e32 v15, v15
	v_rcp_f32_e32 v12, v8
	v_rcp_f32_e32 v13, v9
	v_pk_fma_f32 v[8:9], v[38:39], v[38:39], 1.0 op_sel_hi:[1,1,0] neg_lo:[1,0,0] neg_hi:[1,0,0]
	v_pk_fma_f32 v[2:3], v[2:3], s[36:37], v[70:71] op_sel_hi:[1,0,1] neg_lo:[1,0,0] neg_hi:[1,0,0]
	v_pk_fma_f32 v[0:1], v[0:1], s[36:37], v[68:69] op_sel_hi:[1,0,1] neg_lo:[1,0,0] neg_hi:[1,0,0]
	v_pk_mul_f32 v[22:23], v[66:67], v[22:23]
	v_sqrt_f32_e32 v20, v8
	v_sqrt_f32_e32 v21, v9
	v_pk_mul_f32 v[8:9], v[10:11], v[54:55]
	v_exp_f32_e32 v2, v2
	v_exp_f32_e32 v3, v3
	v_pk_mul_f32 v[6:7], v[66:67], v[6:7]
	v_exp_f32_e32 v0, v0
	v_exp_f32_e32 v1, v1
	v_pk_mul_f32 v[4:5], v[64:65], v[4:5]
	v_exp_f32_e32 v22, v22
	v_exp_f32_e32 v23, v23
	v_pk_mul_f32 v[8:9], v[8:9], v[14:15]
	v_pk_mul_f32 v[10:11], v[12:13], v[52:53]
	v_exp_f32_e32 v12, v6
	v_exp_f32_e32 v13, v7
	v_exp_f32_e32 v14, v4
	v_exp_f32_e32 v15, v5
	v_pk_add_f32 v[2:3], v[2:3], 1.0 op_sel_hi:[1,0]
	v_pk_add_f32 v[0:1], v[0:1], 1.0 op_sel_hi:[1,0]
	v_pk_fma_f32 v[32:33], v[22:23], v[22:23], 1.0 op_sel_hi:[1,1,0] neg_lo:[1,0,0] neg_hi:[1,0,0]
	v_rcp_f32_e32 v2, v2
	v_rcp_f32_e32 v3, v3
	v_pk_fma_f32 v[6:7], v[12:13], v[12:13], 1.0 op_sel_hi:[1,1,0] neg_lo:[1,0,0] neg_hi:[1,0,0]
	v_rcp_f32_e32 v0, v0
	v_rcp_f32_e32 v1, v1
	v_pk_fma_f32 v[4:5], v[14:15], v[14:15], 1.0 op_sel_hi:[1,1,0] neg_lo:[1,0,0] neg_hi:[1,0,0]
	v_sqrt_f32_e32 v32, v32
	v_sqrt_f32_e32 v33, v33
	v_sqrt_f32_e32 v6, v6
	v_sqrt_f32_e32 v7, v7
	v_sqrt_f32_e32 v4, v4
	v_sqrt_f32_e32 v5, v5
	v_pk_mul_f32 v[2:3], v[2:3], v[100:101]
	v_pk_mul_f32 v[0:1], v[0:1], v[98:99]
	v_mov_b32_e32 v78, v26
	v_mov_b32_e32 v79, v31
	v_pk_mul_f32 v[16:17], v[16:17], v[32:33]
	v_mov_b32_e32 v80, v34
	v_mov_b32_e32 v81, v22
	v_pk_mul_f32 v[10:11], v[10:11], v[20:21]
	v_mov_b32_e32 v34, v37
	v_mov_b32_e32 v22, v38
	v_pk_mul_f32 v[20:21], v[2:3], v[6:7]
	v_pk_mul_f32 v[32:33], v[0:1], v[4:5]
	s_nop 1
v_fmac_f32_dpp v28, v28, v30 row_shl:1 row_mask:0xf bank_mask:0xf
v_fmac_f32_dpp v29, v29, v79 row_shl:1 row_mask:0xf bank_mask:0xf
v_fmac_f32_dpp v24, v24, v78 row_shl:1 row_mask:0xf bank_mask:0xf
v_fmac_f32_dpp v25, v25, v27 row_shl:1 row_mask:0xf bank_mask:0xf
v_mul_f32_dpp v30, v30, v30 row_shl:1 row_mask:0xf bank_mask:0xf
v_mul_f32_dpp v79, v79, v79 row_shl:1 row_mask:0xf bank_mask:0xf
v_mul_f32_dpp v78, v78, v78 row_shl:1 row_mask:0xf bank_mask:0xf
v_mul_f32_dpp v27, v27, v27 row_shl:1 row_mask:0xf bank_mask:0xf
v_fmac_f32_dpp v28, v28, v30 row_shl:2 row_mask:0xf bank_mask:0xf
v_fmac_f32_dpp v29, v29, v79 row_shl:2 row_mask:0xf bank_mask:0xf
v_fmac_f32_dpp v24, v24, v78 row_shl:2 row_mask:0xf bank_mask:0xf
v_fmac_f32_dpp v25, v25, v27 row_shl:2 row_mask:0xf bank_mask:0xf
v_mul_f32_dpp v30, v30, v30 row_shl:2 row_mask:0xf bank_mask:0xf
v_mul_f32_dpp v79, v79, v79 row_shl:2 row_mask:0xf bank_mask:0xf
v_mul_f32_dpp v78, v78, v78 row_shl:2 row_mask:0xf bank_mask:0xf
v_mul_f32_dpp v27, v27, v27 row_shl:2 row_mask:0xf bank_mask:0xf
v_fmac_f32_dpp v28, v28, v30 row_shl:4 row_mask:0xf bank_mask:0xf
v_fmac_f32_dpp v29, v29, v79 row_shl:4 row_mask:0xf bank_mask:0xf
v_fmac_f32_dpp v24, v24, v78 row_shl:4 row_mask:0xf bank_mask:0xf
v_fmac_f32_dpp v25, v25, v27 row_shl:4 row_mask:0xf bank_mask:0xf
v_mul_f32_dpp v30, v30, v30 row_shl:4 row_mask:0xf bank_mask:0xf
v_mul_f32_dpp v79, v79, v79 row_shl:4 row_mask:0xf bank_mask:0xf
v_mul_f32_dpp v78, v78, v78 row_shl:4 row_mask:0xf bank_mask:0xf
v_mul_f32_dpp v27, v27, v27 row_shl:4 row_mask:0xf bank_mask:0xf
v_fmac_f32_dpp v28, v28, v30 row_shl:8 row_mask:0xf bank_mask:0xf
v_fmac_f32_dpp v29, v29, v79 row_shl:8 row_mask:0xf bank_mask:0xf
v_fmac_f32_dpp v24, v24, v78 row_shl:8 row_mask:0xf bank_mask:0xf
v_fmac_f32_dpp v25, v25, v27 row_shl:8 row_mask:0xf bank_mask:0xf
v_mul_f32_dpp v30, v30, v30 row_shl:8 row_mask:0xf bank_mask:0xf
v_mul_f32_dpp v79, v79, v79 row_shl:8 row_mask:0xf bank_mask:0xf
v_mul_f32_dpp v78, v78, v78 row_shl:8 row_mask:0xf bank_mask:0xf
v_mul_f32_dpp v27, v27, v27 row_shl:8 row_mask:0xf bank_mask:0xf

	s_nop 1
v_fmac_f32_dpp v18, v18, v80 row_shl:1 row_mask:0xf bank_mask:0xf
v_fmac_f32_dpp v19, v19, v35 row_shl:1 row_mask:0xf bank_mask:0xf
v_fmac_f32_dpp v16, v16, v81 row_shl:1 row_mask:0xf bank_mask:0xf
v_fmac_f32_dpp v17, v17, v23 row_shl:1 row_mask:0xf bank_mask:0xf
v_mul_f32_dpp v80, v80, v80 row_shl:1 row_mask:0xf bank_mask:0xf
v_mul_f32_dpp v35, v35, v35 row_shl:1 row_mask:0xf bank_mask:0xf
v_mul_f32_dpp v81, v81, v81 row_shl:1 row_mask:0xf bank_mask:0xf
v_mul_f32_dpp v23, v23, v23 row_shl:1 row_mask:0xf bank_mask:0xf
v_fmac_f32_dpp v18, v18, v80 row_shl:2 row_mask:0xf bank_mask:0xf
v_fmac_f32_dpp v19, v19, v35 row_shl:2 row_mask:0xf bank_mask:0xf
v_fmac_f32_dpp v16, v16, v81 row_shl:2 row_mask:0xf bank_mask:0xf
v_fmac_f32_dpp v17, v17, v23 row_shl:2 row_mask:0xf bank_mask:0xf
v_mul_f32_dpp v80, v80, v80 row_shl:2 row_mask:0xf bank_mask:0xf
v_mul_f32_dpp v35, v35, v35 row_shl:2 row_mask:0xf bank_mask:0xf
v_mul_f32_dpp v81, v81, v81 row_shl:2 row_mask:0xf bank_mask:0xf
v_mul_f32_dpp v23, v23, v23 row_shl:2 row_mask:0xf bank_mask:0xf
v_fmac_f32_dpp v18, v18, v80 row_shl:4 row_mask:0xf bank_mask:0xf
v_fmac_f32_dpp v19, v19, v35 row_shl:4 row_mask:0xf bank_mask:0xf
v_fmac_f32_dpp v16, v16, v81 row_shl:4 row_mask:0xf bank_mask:0xf
v_fmac_f32_dpp v17, v17, v23 row_shl:4 row_mask:0xf bank_mask:0xf
v_mul_f32_dpp v80, v80, v80 row_shl:4 row_mask:0xf bank_mask:0xf
v_mul_f32_dpp v35, v35, v35 row_shl:4 row_mask:0xf bank_mask:0xf
v_mul_f32_dpp v81, v81, v81 row_shl:4 row_mask:0xf bank_mask:0xf
v_mul_f32_dpp v23, v23, v23 row_shl:4 row_mask:0xf bank_mask:0xf
v_fmac_f32_dpp v18, v18, v80 row_shl:8 row_mask:0xf bank_mask:0xf
v_fmac_f32_dpp v19, v19, v35 row_shl:8 row_mask:0xf bank_mask:0xf
v_fmac_f32_dpp v16, v16, v81 row_shl:8 row_mask:0xf bank_mask:0xf
v_fmac_f32_dpp v17, v17, v23 row_shl:8 row_mask:0xf bank_mask:0xf
v_mul_f32_dpp v80, v80, v80 row_shl:8 row_mask:0xf bank_mask:0xf
v_mul_f32_dpp v35, v35, v35 row_shl:8 row_mask:0xf bank_mask:0xf
v_mul_f32_dpp v81, v81, v81 row_shl:8 row_mask:0xf bank_mask:0xf
v_mul_f32_dpp v23, v23, v23 row_shl:8 row_mask:0xf bank_mask:0xf

	s_nop 1
v_fmac_f32_dpp v10, v10, v22 row_shl:1 row_mask:0xf bank_mask:0xf
v_fmac_f32_dpp v11, v11, v39 row_shl:1 row_mask:0xf bank_mask:0xf
v_fmac_f32_dpp v8, v8, v36 row_shl:1 row_mask:0xf bank_mask:0xf
v_fmac_f32_dpp v9, v9, v34 row_shl:1 row_mask:0xf bank_mask:0xf
v_mul_f32_dpp v22, v22, v22 row_shl:1 row_mask:0xf bank_mask:0xf
v_mul_f32_dpp v39, v39, v39 row_shl:1 row_mask:0xf bank_mask:0xf
v_mul_f32_dpp v36, v36, v36 row_shl:1 row_mask:0xf bank_mask:0xf
v_mul_f32_dpp v34, v34, v34 row_shl:1 row_mask:0xf bank_mask:0xf
v_fmac_f32_dpp v10, v10, v22 row_shl:2 row_mask:0xf bank_mask:0xf
v_fmac_f32_dpp v11, v11, v39 row_shl:2 row_mask:0xf bank_mask:0xf
v_fmac_f32_dpp v8, v8, v36 row_shl:2 row_mask:0xf bank_mask:0xf
v_fmac_f32_dpp v9, v9, v34 row_shl:2 row_mask:0xf bank_mask:0xf
v_mul_f32_dpp v22, v22, v22 row_shl:2 row_mask:0xf bank_mask:0xf
v_mul_f32_dpp v39, v39, v39 row_shl:2 row_mask:0xf bank_mask:0xf
v_mul_f32_dpp v36, v36, v36 row_shl:2 row_mask:0xf bank_mask:0xf
v_mul_f32_dpp v34, v34, v34 row_shl:2 row_mask:0xf bank_mask:0xf
v_fmac_f32_dpp v10, v10, v22 row_shl:4 row_mask:0xf bank_mask:0xf
v_fmac_f32_dpp v11, v11, v39 row_shl:4 row_mask:0xf bank_mask:0xf
v_fmac_f32_dpp v8, v8, v36 row_shl:4 row_mask:0xf bank_mask:0xf
v_fmac_f32_dpp v9, v9, v34 row_shl:4 row_mask:0xf bank_mask:0xf
v_mul_f32_dpp v22, v22, v22 row_shl:4 row_mask:0xf bank_mask:0xf
v_mul_f32_dpp v39, v39, v39 row_shl:4 row_mask:0xf bank_mask:0xf
v_mul_f32_dpp v36, v36, v36 row_shl:4 row_mask:0xf bank_mask:0xf
v_mul_f32_dpp v34, v34, v34 row_shl:4 row_mask:0xf bank_mask:0xf
v_fmac_f32_dpp v10, v10, v22 row_shl:8 row_mask:0xf bank_mask:0xf
v_fmac_f32_dpp v11, v11, v39 row_shl:8 row_mask:0xf bank_mask:0xf
v_fmac_f32_dpp v8, v8, v36 row_shl:8 row_mask:0xf bank_mask:0xf
v_fmac_f32_dpp v9, v9, v34 row_shl:8 row_mask:0xf bank_mask:0xf
v_mul_f32_dpp v22, v22, v22 row_shl:8 row_mask:0xf bank_mask:0xf
v_mul_f32_dpp v39, v39, v39 row_shl:8 row_mask:0xf bank_mask:0xf
v_mul_f32_dpp v36, v36, v36 row_shl:8 row_mask:0xf bank_mask:0xf
v_mul_f32_dpp v34, v34, v34 row_shl:8 row_mask:0xf bank_mask:0xf

	s_nop 0
	s_nop 1
v_fmac_f32_dpp v32, v32, v14 row_shl:1 row_mask:0xf bank_mask:0xf
v_fmac_f32_dpp v33, v33, v15 row_shl:1 row_mask:0xf bank_mask:0xf
v_fmac_f32_dpp v20, v20, v12 row_shl:1 row_mask:0xf bank_mask:0xf
v_fmac_f32_dpp v21, v21, v13 row_shl:1 row_mask:0xf bank_mask:0xf
v_mul_f32_dpp v14, v14, v14 row_shl:1 row_mask:0xf bank_mask:0xf
v_mul_f32_dpp v15, v15, v15 row_shl:1 row_mask:0xf bank_mask:0xf
v_mul_f32_dpp v12, v12, v12 row_shl:1 row_mask:0xf bank_mask:0xf
v_mul_f32_dpp v13, v13, v13 row_shl:1 row_mask:0xf bank_mask:0xf
v_fmac_f32_dpp v32, v32, v14 row_shl:2 row_mask:0xf bank_mask:0xf
v_fmac_f32_dpp v33, v33, v15 row_shl:2 row_mask:0xf bank_mask:0xf
v_fmac_f32_dpp v20, v20, v12 row_shl:2 row_mask:0xf bank_mask:0xf
v_fmac_f32_dpp v21, v21, v13 row_shl:2 row_mask:0xf bank_mask:0xf
v_mul_f32_dpp v14, v14, v14 row_shl:2 row_mask:0xf bank_mask:0xf
v_mul_f32_dpp v15, v15, v15 row_shl:2 row_mask:0xf bank_mask:0xf
v_mul_f32_dpp v12, v12, v12 row_shl:2 row_mask:0xf bank_mask:0xf
v_mul_f32_dpp v13, v13, v13 row_shl:2 row_mask:0xf bank_mask:0xf
v_fmac_f32_dpp v32, v32, v14 row_shl:4 row_mask:0xf bank_mask:0xf
v_fmac_f32_dpp v33, v33, v15 row_shl:4 row_mask:0xf bank_mask:0xf
v_fmac_f32_dpp v20, v20, v12 row_shl:4 row_mask:0xf bank_mask:0xf
v_fmac_f32_dpp v21, v21, v13 row_shl:4 row_mask:0xf bank_mask:0xf
v_mul_f32_dpp v14, v14, v14 row_shl:4 row_mask:0xf bank_mask:0xf
v_mul_f32_dpp v15, v15, v15 row_shl:4 row_mask:0xf bank_mask:0xf
v_mul_f32_dpp v12, v12, v12 row_shl:4 row_mask:0xf bank_mask:0xf
v_mul_f32_dpp v13, v13, v13 row_shl:4 row_mask:0xf bank_mask:0xf
v_fmac_f32_dpp v32, v32, v14 row_shl:8 row_mask:0xf bank_mask:0xf
v_fmac_f32_dpp v33, v33, v15 row_shl:8 row_mask:0xf bank_mask:0xf
v_fmac_f32_dpp v20, v20, v12 row_shl:8 row_mask:0xf bank_mask:0xf
v_fmac_f32_dpp v21, v21, v13 row_shl:8 row_mask:0xf bank_mask:0xf
v_mul_f32_dpp v14, v14, v14 row_shl:8 row_mask:0xf bank_mask:0xf
v_mul_f32_dpp v15, v15, v15 row_shl:8 row_mask:0xf bank_mask:0xf
v_mul_f32_dpp v12, v12, v12 row_shl:8 row_mask:0xf bank_mask:0xf
v_mul_f32_dpp v13, v13, v13 row_shl:8 row_mask:0xf bank_mask:0xf

	ds_bpermute_b32 v1, v144, v14
	v_fmac_f32_e32 v32, 0, v14
	v_fmac_f32_e32 v33, 0, v15
	v_fmac_f32_e32 v20, 0, v12
	v_fmac_f32_e32 v21, 0, v13
	ds_bpermute_b32 v0, v144, v32
	ds_bpermute_b32 v2, v144, v33
	ds_bpermute_b32 v3, v144, v15
	ds_bpermute_b32 v4, v144, v20
	ds_bpermute_b32 v5, v144, v12
	ds_bpermute_b32 v6, v144, v21
	ds_bpermute_b32 v7, v144, v13
	s_waitcnt lgkmcnt(0)
	v_fmac_f32_e32 v10, v22, v0
	v_mul_f32_e32 v22, v22, v1
	v_fmac_f32_e32 v11, v39, v2
	v_mul_f32_e32 v26, v39, v3
	v_fmac_f32_e32 v8, v36, v4
	v_mul_f32_e32 v31, v36, v5
	v_fmac_f32_e32 v9, v34, v6
	v_mul_f32_e32 v34, v34, v7
	ds_bpermute_b32 v0, v144, v10
	ds_bpermute_b32 v1, v144, v22
	ds_bpermute_b32 v2, v144, v11
	ds_bpermute_b32 v3, v144, v26
	ds_bpermute_b32 v4, v144, v8
	ds_bpermute_b32 v5, v144, v31
	ds_bpermute_b32 v6, v144, v9
	ds_bpermute_b32 v7, v144, v34
	s_waitcnt lgkmcnt(0)
	v_fmac_f32_e32 v18, v80, v0
	v_mul_f32_e32 v36, v80, v1
	v_fmac_f32_e32 v19, v35, v2
	v_mul_f32_e32 v35, v35, v3
	v_fmac_f32_e32 v16, v81, v4
	v_mul_f32_e32 v37, v81, v5
	v_fmac_f32_e32 v17, v23, v6
	v_mul_f32_e32 v23, v23, v7
	ds_bpermute_b32 v0, v144, v18
	ds_bpermute_b32 v1, v144, v36
	ds_bpermute_b32 v2, v144, v19
	ds_bpermute_b32 v3, v144, v35
	ds_bpermute_b32 v4, v144, v16
	ds_bpermute_b32 v5, v144, v37
	ds_bpermute_b32 v6, v144, v17
	ds_bpermute_b32 v7, v144, v23
	s_waitcnt lgkmcnt(0)
	v_fmac_f32_e32 v28, v30, v0
	v_mul_f32_e32 v30, v30, v1
	v_fmac_f32_e32 v29, v79, v2
	v_mul_f32_e32 v38, v79, v3
	v_fmac_f32_e32 v24, v78, v4
	v_mul_f32_e32 v39, v78, v5
	v_fmac_f32_e32 v25, v27, v6
	v_mul_f32_e32 v27, v27, v7
	v_mov_b32_e32 v1, v28
	v_mov_b32_e32 v0, v30
	v_mov_b32_e32 v3, v29
	v_mov_b32_e32 v2, v38
	v_mov_b32_e32 v5, v24
	v_mov_b32_e32 v4, v39
	v_mov_b32_e32 v7, v25
	v_mov_b32_e32 v6, v27
	s_and_saveexec_b64 s[10:11], s[12:13]
	s_cbranch_execz .LBB0_445
	s_or_b32 s4, s47, 1
	s_mul_hi_i32 s5, s4, 0x84
	s_mulk_i32 s4, 0x84
	s_add_u32 s4, s4, s49
	s_addc_u32 s5, s5, 0
	s_mulk_i32 s5, 0x2800
	s_mul_hi_u32 s12, s4, 0x2800
	s_add_i32 s12, s12, s5
	s_mulk_i32 s4, 0x2800
	s_add_u32 s4, s77, s4
	s_addc_u32 s5, s78, s12
	v_lshl_add_u64 v[52:53], v[176:177], 3, s[4:5]
	s_waitcnt lgkmcnt(0)
	flat_store_dwordx4 v[52:53], v[0:3]
	flat_store_dwordx4 v[52:53], v[4:7] offset:16
	s_or_b64 exec, exec, s[10:11]
	s_and_b64 vcc, exec, s[14:15]
	s_cbranch_vccnz .LBB0_447
	s_branch .LBB0_446
